# v45 plus: first loop iteration of every GEMM unit peeled (w_in, w_out, down, up) with the inline constant 0 as C of the first MFMA into each accumulator; the 128 accumulator-clearing v_mov per unit re
# speedup vs baseline: 1.0095x; 1.0012x over previous
; template <class Epi, class Sched, bool ALIGN_EPI = false, bool SP2 = false>
; __device__ __forceinline__ void gemm_phase(PG8_LAS unsigned char* lds, const Gemm g, const Sched& S, const Epi& E) {
;     ...
; #pragma unroll
;         for (int a = 0; a < 2; ++a)
; #pragma unroll
;             for (int b = 0; b < 2; ++b)
; #pragma unroll
;                 for (int m = 0; m < 4; ++m)
; #pragma unroll
;                     for (int n = 0; n < 2; ++n) acc[a][b][m][n] = (f32x4){0.f, 0.f, 0.f, 0.f};
;         cur = nxt; cA = nA; cB = nB; ++ui;
.LBB0_166:
	s_mov_b32 s75, s62
	s_mov_b32 s86, s68
	s_mov_b64 s[70:71], s[76:77]
	s_mov_b32 s87, s92
	s_andn2_b64 vcc, exec, s[78:79]
	s_mov_b64 s[46:47], s[72:73]
	s_cbranch_vccz .LBB0_209

; #define PG8_STAGE(bufoff, gbase, voff) do { _Pragma("unroll") for (int _i = 0; _i < 2; ++_i) \
;         __builtin_amdgcn_global_load_lds((const unsigned*)((const char*)(gbase) + (voff)[_i]), (PG8_LAS unsigned*)(lds + (bufoff) + ldsw + _i * 8192), 16, 0, 0); } while (0)
; #define PG8_LDA(dst, b, h) do { _Pragma("unroll") for (int m = 0; m < 4; ++m) _Pragma("unroll") for (int k = 0; k < 2; ++k) dst[m][k] = *(const PG8_LAS bf16x8*)(lds + PG8_SA(b, h) + aoff + m * 2048 + k * 1024); } while (0)
; #define PG8_LDB(dst, b, h) do { _Pragma("unroll") for (int n = 0; n < 2; ++n) _Pragma("unroll") for (int k = 0; k < 2; ++k) dst[n][k] = *(const PG8_LAS bf16x8*)(lds + PG8_SB(b, h) + boff + n * 2048 + k * 1024); } while (0)
; #define PG8_WAIT_V(n) asm volatile("s_waitcnt vmcnt(" #n ")" ::: "memory")
; #define PG8_WAIT_L(n) asm volatile("s_waitcnt lgkmcnt(" #n ")" ::: "memory")
; #define PG8_BAR __builtin_amdgcn_s_barrier()
; #define PG8_SCHED __builtin_amdgcn_sched_barrier(0)
; template <class Epi, class Sched, bool ALIGN_EPI = false, bool SP2 = false>
; __device__ __forceinline__ void gemm_phase(PG8_LAS unsigned char* lds, const Gemm g, const Sched& S, const Epi& E) {
;     ...
;         const bool has_next = S.next(ui + 1, nxt);
;         const char* nA = has_next ? (const char*)g.A + (size_t)nxt.pm * tstep : cA; const char* nB = has_next ? (const char*)g.Bt + (size_t)nxt.pn * tstep : cB;
;         for (int t = 0; t < nt; t += 2) {
;             const bool last = (t == nt - 2);
;             const char* a1 = cA + (size_t)(t + 1) * kstep;
;             const char* a2 = last ? nA : cA + (size_t)(t + 2) * kstep; const char* b2 = last ? nB : cB + (size_t)(t + 2) * kstep;
;             const char* a3 = a2 + kstep; const char* b3 = b2 + kstep;
;             if (last && has_next) S.a_ready(nxt);
;             if constexpr (SP2) {
;             PG8_LDB(B0, 0, 0); PG8_LDB(B1, 0, 1); PG8_SCHED; PG8_LDA(At, 0, 0); PG8_STAGE(PG8_SA(1, 1), a1 + hstep, voffA);
;             PG8_WAIT_V(8); PG8_WAIT_L(0); PG8_BAR; PG8_MMA(0, 0, At, B0); PG8_MMA(0, 1, At, B1); PG8_BAR; PG8_SCHED;
;             PG8_LDA(At, 0, 1); PG8_STAGE(PG8_SB(0, 0), b2, voffB); PG8_STAGE(PG8_SB(0, 1), b2 + hstepB, voffB); PG8_STAGE(PG8_SA(0, 0), a2, voffA);
;             PG8_WAIT_V(8); PG8_WAIT_L(0); PG8_BAR; PG8_MMA(1, 0, At, B0); PG8_MMA(1, 1, At, B1); PG8_BAR; PG8_SCHED;
.LBB0_169:
	s_add_u32 s93, s46, 0x100
	s_addc_u32 s94, s47, 0
	s_ashr_i32 s69, s68, 31
	s_lshl_b64 s[4:5], s[68:69], 20
	s_add_u32 s76, s52, s4
	s_addc_u32 s77, s53, s5
	s_and_b64 s[4:5], s[38:39], exec
	s_cselect_b32 s4, s77, s71
	s_cselect_b32 s5, s76, s70
	s_ashr_i32 s63, s62, 31
	s_lshl_b64 s[6:7], s[62:63], 20
	v_readlane_b32 s8, v249, 19
	v_readlane_b32 s9, v249, 20
	s_add_u32 s72, s8, s6
	s_addc_u32 s73, s9, s7
	s_and_b64 s[6:7], s[38:39], exec
	s_cselect_b32 s6, s73, s47
	s_cselect_b32 s7, s72, s46
	s_add_u32 s8, s70, 0x80080
	s_addc_u32 s9, s71, 0
	v_lshl_add_u64 v[144:145], s[8:9], 0, v[140:141]
	v_lshl_add_u64 v[146:147], s[8:9], 0, v[142:143]
	s_mov_b32 s8, -2
	s_mov_b64 s[46:47], 0
	v_add_u32_e32 v186, 0x10000, v139
	v_add_u32_e32 v187, 0x14000, v139
	v_add_u32_e32 v198, 0x18000, v139
	v_add_u32_e32 v199, 0x1c000, v139
	s_add_u32 s9, s70, s46
	s_addc_u32 s10, s71, s47
	s_add_u32 s9, s9, 0x100
	s_addc_u32 s10, s10, 0
	s_add_u32 s100, s9, 0x7ff80
	s_addc_u32 s101, s10, 0
	s_add_u32 s11, s93, s46
	s_addc_u32 s12, s94, s47
	s_add_i32 s13, 0, 0x10000
	s_cmpk_eq_i32 s46, 0xf00
	s_cselect_b32 s85, s4, s10
	s_cselect_b32 s84, s5, s9
	s_cselect_b32 s81, s6, s12
	s_cselect_b32 s80, s7, s11
	s_add_i32 s9, 0, 0x14000
	ds_read_b128 v[148:151], v186
	ds_read_b128 v[152:155], v186 offset:1024
	ds_read_b128 v[156:159], v186 offset:2048
	ds_read_b128 v[160:163], v186 offset:3072
	ds_read_b128 v[166:169], v187
	ds_read_b128 v[170:173], v187 offset:1024
	ds_read_b128 v[174:177], v187 offset:2048
	ds_read_b128 v[178:181], v187 offset:3072
	s_add_i32 m0, s1, 0xc000
	ds_read_b128 v[182:185], v165
	ds_read_b128 v[206:209], v165 offset:1024
	ds_read_b128 v[210:213], v165 offset:2048
	ds_read_b128 v[214:217], v165 offset:3072
	ds_read_b128 v[218:221], v165 offset:4096
	ds_read_b128 v[236:239], v165 offset:5120
	ds_read_b128 v[240:243], v165 offset:6144
	ds_read_b128 v[244:247], v165 offset:7168
	global_load_lds_dwordx4 v140, s[100:101]
	s_add_i32 m0, s1, 0xe000
	s_nop 0
	global_load_lds_dwordx4 v142, s[100:101]
	s_waitcnt vmcnt(8)
	s_waitcnt lgkmcnt(0)
	s_barrier
	v_mfma_f32_16x16x32_bf16 v[126:129], v[148:151], v[182:185], 0
	v_mfma_f32_16x16x32_bf16 v[122:125], v[156:159], v[182:185], 0
	v_mfma_f32_16x16x32_bf16 v[118:121], v[148:151], v[210:213], 0
	v_mfma_f32_16x16x32_bf16 v[114:117], v[156:159], v[210:213], 0
	v_mfma_f32_16x16x32_bf16 v[110:113], v[148:151], v[218:221], 0
	v_mfma_f32_16x16x32_bf16 v[106:109], v[156:159], v[218:221], 0
	v_mfma_f32_16x16x32_bf16 v[102:105], v[148:151], v[240:243], 0
	v_mfma_f32_16x16x32_bf16 v[98:101], v[156:159], v[240:243], 0
	v_mfma_f32_16x16x32_bf16 v[126:129], v[152:155], v[206:209], v[126:129]
	v_mfma_f32_16x16x32_bf16 v[122:125], v[160:163], v[206:209], v[122:125]
	v_mfma_f32_16x16x32_bf16 v[118:121], v[152:155], v[214:217], v[118:121]
	v_mfma_f32_16x16x32_bf16 v[114:117], v[160:163], v[214:217], v[114:117]
	v_mfma_f32_16x16x32_bf16 v[110:113], v[152:155], v[236:239], v[110:113]
	v_mfma_f32_16x16x32_bf16 v[106:109], v[160:163], v[236:239], v[106:109]
	v_mfma_f32_16x16x32_bf16 v[102:105], v[152:155], v[244:247], v[102:105]
	v_mfma_f32_16x16x32_bf16 v[98:101], v[160:163], v[244:247], v[98:101]
	v_mfma_f32_16x16x32_bf16 v[94:97], v[166:169], v[182:185], 0
	v_mfma_f32_16x16x32_bf16 v[90:93], v[174:177], v[182:185], 0
	v_mfma_f32_16x16x32_bf16 v[86:89], v[166:169], v[210:213], 0
	v_mfma_f32_16x16x32_bf16 v[82:85], v[174:177], v[210:213], 0
	v_mfma_f32_16x16x32_bf16 v[78:81], v[166:169], v[218:221], 0
	v_mfma_f32_16x16x32_bf16 v[74:77], v[174:177], v[218:221], 0
	v_mfma_f32_16x16x32_bf16 v[70:73], v[166:169], v[240:243], 0
	v_mfma_f32_16x16x32_bf16 v[66:69], v[174:177], v[240:243], 0
	v_mfma_f32_16x16x32_bf16 v[94:97], v[170:173], v[206:209], v[94:97]
	v_mfma_f32_16x16x32_bf16 v[90:93], v[178:181], v[206:209], v[90:93]
	v_mfma_f32_16x16x32_bf16 v[86:89], v[170:173], v[214:217], v[86:89]
	v_mfma_f32_16x16x32_bf16 v[82:85], v[178:181], v[214:217], v[82:85]
	v_mfma_f32_16x16x32_bf16 v[78:81], v[170:173], v[236:239], v[78:81]
	v_mfma_f32_16x16x32_bf16 v[74:77], v[178:181], v[236:239], v[74:77]
	v_mfma_f32_16x16x32_bf16 v[70:73], v[170:173], v[244:247], v[70:73]
	v_mfma_f32_16x16x32_bf16 v[66:69], v[178:181], v[244:247], v[66:69]
	s_barrier
	s_add_i32 s10, s13, s0
	s_mov_b32 m0, s10
	ds_read_b128 v[182:185], v165 offset:16384
	ds_read_b128 v[206:209], v165 offset:17408
	ds_read_b128 v[210:213], v165 offset:18432
	ds_read_b128 v[214:217], v165 offset:19456
	ds_read_b128 v[218:221], v165 offset:20480
	ds_read_b128 v[236:239], v165 offset:21504
	ds_read_b128 v[240:243], v165 offset:22528
	ds_read_b128 v[244:247], v165 offset:23552
	global_load_lds_dwordx4 v132, s[80:81]
	s_add_i32 m0, s10, 0x2000
	s_add_u32 s10, s80, 0x20000
	s_addc_u32 s11, s81, 0
	s_add_i32 s9, s9, s0
	global_load_lds_dwordx4 v136, s[80:81]
	s_mov_b32 m0, s9
	s_nop 0
	global_load_lds_dwordx4 v132, s[10:11]
	s_add_i32 m0, s9, 0x2000
	s_nop 0
	global_load_lds_dwordx4 v136, s[10:11]
	s_mov_b32 m0, s1
	s_nop 0
	global_load_lds_dwordx4 v130, s[84:85]
	s_mov_b32 m0, s25
	s_nop 0
	global_load_lds_dwordx4 v134, s[84:85]
	s_waitcnt vmcnt(8)
	s_waitcnt lgkmcnt(0)
	s_barrier
; #define PG8_STAGE(bufoff, gbase, voff) do { _Pragma("unroll") for (int _i = 0; _i < 2; ++_i) \
;         __builtin_amdgcn_global_load_lds((const unsigned*)((const char*)(gbase) + (voff)[_i]), (PG8_LAS unsigned*)(lds + (bufoff) + ldsw + _i * 8192), 16, 0, 0); } while (0)
; #define PG8_LDA(dst, b, h) do { _Pragma("unroll") for (int m = 0; m < 4; ++m) _Pragma("unroll") for (int k = 0; k < 2; ++k) dst[m][k] = *(const PG8_LAS bf16x8*)(lds + PG8_SA(b, h) + aoff + m * 2048 + k * 1024); } while (0)
; #define PG8_LDB(dst, b, h) do { _Pragma("unroll") for (int n = 0; n < 2; ++n) _Pragma("unroll") for (int k = 0; k < 2; ++k) dst[n][k] = *(const PG8_LAS bf16x8*)(lds + PG8_SB(b, h) + boff + n * 2048 + k * 1024); } while (0)
; #define PG8_MMA(ai, bj, At, Bt) do { __builtin_amdgcn_s_setprio(1); _Pragma("unroll") for (int m = 0; m < 4; ++m) _Pragma("unroll") for (int n = 0; n < 2; ++n) _Pragma("unroll") for (int k = 0; k < 2; ++k) \
;         acc[ai][bj][m][n] = __builtin_amdgcn_mfma_f32_16x16x32_bf16(Bt[n][k], At[m][k], acc[ai][bj][m][n], 0, 0, 0); __builtin_amdgcn_s_setprio(0); } while (0)
; #define PG8_WAIT_V(n) asm volatile("s_waitcnt vmcnt(" #n ")" ::: "memory")
; #define PG8_WAIT_L(n) asm volatile("s_waitcnt lgkmcnt(" #n ")" ::: "memory")
; #define PG8_BAR __builtin_amdgcn_s_barrier()
; #define PG8_SCHED __builtin_amdgcn_sched_barrier(0)
; template <class Epi, class Sched, bool ALIGN_EPI = false, bool SP2 = false>
; __device__ __forceinline__ void gemm_phase(PG8_LAS unsigned char* lds, const Gemm g, const Sched& S, const Epi& E) {
;     ...
;             PG8_WAIT_V(8); PG8_WAIT_L(0); PG8_BAR; PG8_MMA(1, 0, At, B0); PG8_MMA(1, 1, At, B1); PG8_BAR; PG8_SCHED;
;             PG8_LDB(B0, 1, 0); PG8_LDB(B1, 1, 1); PG8_SCHED; PG8_LDA(At, 1, 0); PG8_STAGE(PG8_SA(0, 1), a2 + hstep, voffA);
;             PG8_WAIT_V(8); PG8_WAIT_L(0); PG8_BAR; PG8_MMA(0, 0, At, B0); PG8_MMA(0, 1, At, B1); PG8_BAR; PG8_SCHED;
	v_mfma_f32_16x16x32_bf16 v[62:65], v[148:151], v[182:185], 0
	v_mfma_f32_16x16x32_bf16 v[58:61], v[156:159], v[182:185], 0
	v_mfma_f32_16x16x32_bf16 v[54:57], v[148:151], v[210:213], 0
	v_mfma_f32_16x16x32_bf16 v[50:53], v[156:159], v[210:213], 0
	v_mfma_f32_16x16x32_bf16 v[46:49], v[148:151], v[218:221], 0
	v_mfma_f32_16x16x32_bf16 v[42:45], v[156:159], v[218:221], 0
	v_mfma_f32_16x16x32_bf16 v[38:41], v[148:151], v[240:243], 0
	v_mfma_f32_16x16x32_bf16 v[34:37], v[156:159], v[240:243], 0
	v_mfma_f32_16x16x32_bf16 v[62:65], v[152:155], v[206:209], v[62:65]
	v_mfma_f32_16x16x32_bf16 v[58:61], v[160:163], v[206:209], v[58:61]
	v_mfma_f32_16x16x32_bf16 v[54:57], v[152:155], v[214:217], v[54:57]
	v_mfma_f32_16x16x32_bf16 v[50:53], v[160:163], v[214:217], v[50:53]
	v_mfma_f32_16x16x32_bf16 v[46:49], v[152:155], v[236:239], v[46:49]
	v_mfma_f32_16x16x32_bf16 v[42:45], v[160:163], v[236:239], v[42:45]
	v_mfma_f32_16x16x32_bf16 v[38:41], v[152:155], v[244:247], v[38:41]
	v_mfma_f32_16x16x32_bf16 v[34:37], v[160:163], v[244:247], v[34:37]
	v_mfma_f32_16x16x32_bf16 v[30:33], v[166:169], v[182:185], 0
	v_mfma_f32_16x16x32_bf16 v[26:29], v[174:177], v[182:185], 0
	v_mfma_f32_16x16x32_bf16 v[22:25], v[166:169], v[210:213], 0
	v_mfma_f32_16x16x32_bf16 v[18:21], v[174:177], v[210:213], 0
	v_mfma_f32_16x16x32_bf16 v[14:17], v[166:169], v[218:221], 0
	v_mfma_f32_16x16x32_bf16 v[10:13], v[174:177], v[218:221], 0
	v_mfma_f32_16x16x32_bf16 v[6:9], v[166:169], v[240:243], 0
	v_mfma_f32_16x16x32_bf16 v[2:5], v[174:177], v[240:243], 0
	v_mfma_f32_16x16x32_bf16 v[30:33], v[170:173], v[206:209], v[30:33]
	v_mfma_f32_16x16x32_bf16 v[26:29], v[178:181], v[206:209], v[26:29]
	v_mfma_f32_16x16x32_bf16 v[22:25], v[170:173], v[214:217], v[22:25]
	v_mfma_f32_16x16x32_bf16 v[18:21], v[178:181], v[214:217], v[18:21]
	v_mfma_f32_16x16x32_bf16 v[14:17], v[170:173], v[236:239], v[14:17]
	v_mfma_f32_16x16x32_bf16 v[10:13], v[178:181], v[236:239], v[10:13]
	v_mfma_f32_16x16x32_bf16 v[6:9], v[170:173], v[244:247], v[6:9]
	v_mfma_f32_16x16x32_bf16 v[2:5], v[178:181], v[244:247], v[2:5]
	s_barrier
	s_add_i32 s9, 0, 0x18000
	s_add_i32 s12, 0, 0x1c000
	ds_read_b128 v[148:151], v198
	ds_read_b128 v[152:155], v198 offset:1024
	ds_read_b128 v[156:159], v198 offset:2048
	ds_read_b128 v[160:163], v198 offset:3072
	ds_read_b128 v[166:169], v199
	ds_read_b128 v[170:173], v199 offset:1024
	ds_read_b128 v[174:177], v199 offset:2048
	ds_read_b128 v[178:181], v199 offset:3072
	s_add_u32 s10, s84, 0x80000
	s_addc_u32 s11, s85, 0
	s_mov_b32 m0, s42
	ds_read_b128 v[182:185], v165 offset:32768
	ds_read_b128 v[206:209], v165 offset:33792
	ds_read_b128 v[210:213], v165 offset:34816
	ds_read_b128 v[214:217], v165 offset:35840
	ds_read_b128 v[218:221], v165 offset:36864
	ds_read_b128 v[236:239], v165 offset:37888
	ds_read_b128 v[240:243], v165 offset:38912
	ds_read_b128 v[244:247], v165 offset:39936
	global_load_lds_dwordx4 v130, s[10:11]
	s_mov_b32 m0, s51
	s_nop 0
	global_load_lds_dwordx4 v134, s[10:11]
	s_waitcnt vmcnt(8)
	s_waitcnt lgkmcnt(0)
	s_barrier
	v_mfma_f32_16x16x32_bf16 v[126:129], v[148:151], v[182:185], v[126:129]
	v_mfma_f32_16x16x32_bf16 v[122:125], v[156:159], v[182:185], v[122:125]
	v_mfma_f32_16x16x32_bf16 v[118:121], v[148:151], v[210:213], v[118:121]
	v_mfma_f32_16x16x32_bf16 v[114:117], v[156:159], v[210:213], v[114:117]
	v_mfma_f32_16x16x32_bf16 v[110:113], v[148:151], v[218:221], v[110:113]
	v_mfma_f32_16x16x32_bf16 v[106:109], v[156:159], v[218:221], v[106:109]
	v_mfma_f32_16x16x32_bf16 v[102:105], v[148:151], v[240:243], v[102:105]
	v_mfma_f32_16x16x32_bf16 v[98:101], v[156:159], v[240:243], v[98:101]
	v_mfma_f32_16x16x32_bf16 v[126:129], v[152:155], v[206:209], v[126:129]
	v_mfma_f32_16x16x32_bf16 v[122:125], v[160:163], v[206:209], v[122:125]
	v_mfma_f32_16x16x32_bf16 v[118:121], v[152:155], v[214:217], v[118:121]
	v_mfma_f32_16x16x32_bf16 v[114:117], v[160:163], v[214:217], v[114:117]
	v_mfma_f32_16x16x32_bf16 v[110:113], v[152:155], v[236:239], v[110:113]
	v_mfma_f32_16x16x32_bf16 v[106:109], v[160:163], v[236:239], v[106:109]
	v_mfma_f32_16x16x32_bf16 v[102:105], v[152:155], v[244:247], v[102:105]
	v_mfma_f32_16x16x32_bf16 v[98:101], v[160:163], v[244:247], v[98:101]
	v_mfma_f32_16x16x32_bf16 v[94:97], v[166:169], v[182:185], v[94:97]
	v_mfma_f32_16x16x32_bf16 v[90:93], v[174:177], v[182:185], v[90:93]
	v_mfma_f32_16x16x32_bf16 v[86:89], v[166:169], v[210:213], v[86:89]
	v_mfma_f32_16x16x32_bf16 v[82:85], v[174:177], v[210:213], v[82:85]
	v_mfma_f32_16x16x32_bf16 v[78:81], v[166:169], v[218:221], v[78:81]
	v_mfma_f32_16x16x32_bf16 v[74:77], v[174:177], v[218:221], v[74:77]
	v_mfma_f32_16x16x32_bf16 v[70:73], v[166:169], v[240:243], v[70:73]
	v_mfma_f32_16x16x32_bf16 v[66:69], v[174:177], v[240:243], v[66:69]
	v_mfma_f32_16x16x32_bf16 v[94:97], v[170:173], v[206:209], v[94:97]
	v_mfma_f32_16x16x32_bf16 v[90:93], v[178:181], v[206:209], v[90:93]
	v_mfma_f32_16x16x32_bf16 v[86:89], v[170:173], v[214:217], v[86:89]
	v_mfma_f32_16x16x32_bf16 v[82:85], v[178:181], v[214:217], v[82:85]
	v_mfma_f32_16x16x32_bf16 v[78:81], v[170:173], v[236:239], v[78:81]
	v_mfma_f32_16x16x32_bf16 v[74:77], v[178:181], v[236:239], v[74:77]
	v_mfma_f32_16x16x32_bf16 v[70:73], v[170:173], v[244:247], v[70:73]
	v_mfma_f32_16x16x32_bf16 v[66:69], v[178:181], v[244:247], v[66:69]
	s_barrier
; #define PG8_STAGE(bufoff, gbase, voff) do { _Pragma("unroll") for (int _i = 0; _i < 2; ++_i) \
;         __builtin_amdgcn_global_load_lds((const unsigned*)((const char*)(gbase) + (voff)[_i]), (PG8_LAS unsigned*)(lds + (bufoff) + ldsw + _i * 8192), 16, 0, 0); } while (0)
; #define PG8_LDA(dst, b, h) do { _Pragma("unroll") for (int m = 0; m < 4; ++m) _Pragma("unroll") for (int k = 0; k < 2; ++k) dst[m][k] = *(const PG8_LAS bf16x8*)(lds + PG8_SA(b, h) + aoff + m * 2048 + k * 1024); } while (0)
; #define PG8_MMA(ai, bj, At, Bt) do { __builtin_amdgcn_s_setprio(1); _Pragma("unroll") for (int m = 0; m < 4; ++m) _Pragma("unroll") for (int n = 0; n < 2; ++n) _Pragma("unroll") for (int k = 0; k < 2; ++k) \
;         acc[ai][bj][m][n] = __builtin_amdgcn_mfma_f32_16x16x32_bf16(Bt[n][k], At[m][k], acc[ai][bj][m][n], 0, 0, 0); __builtin_amdgcn_s_setprio(0); } while (0)
; #define PG8_WAIT_V(n) asm volatile("s_waitcnt vmcnt(" #n ")" ::: "memory")
; #define PG8_WAIT_L(n) asm volatile("s_waitcnt lgkmcnt(" #n ")" ::: "memory")
; #define PG8_BAR __builtin_amdgcn_s_barrier()
; #define PG8_SCHED __builtin_amdgcn_sched_barrier(0)
; template <class Epi, class Sched, bool ALIGN_EPI = false, bool SP2 = false>
; __device__ __forceinline__ void gemm_phase(PG8_LAS unsigned char* lds, const Gemm g, const Sched& S, const Epi& E) {
;     ...
;             PG8_LDA(At, 1, 1); PG8_STAGE(PG8_SB(1, 0), b3, voffB); PG8_STAGE(PG8_SB(1, 1), b3 + hstepB, voffB); PG8_STAGE(PG8_SA(1, 0), a3, voffA);
;             PG8_WAIT_V(8); PG8_WAIT_L(0); PG8_BAR; PG8_MMA(1, 0, At, B0); PG8_MMA(1, 1, At, B1); PG8_BAR; PG8_SCHED;
	s_add_i32 s9, s9, s0
	s_mov_b32 m0, s9
	ds_read_b128 v[182:185], v165 offset:49152
	ds_read_b128 v[206:209], v165 offset:50176
	ds_read_b128 v[210:213], v165 offset:51200
	ds_read_b128 v[214:217], v165 offset:52224
	ds_read_b128 v[218:221], v165 offset:53248
	ds_read_b128 v[236:239], v165 offset:54272
	ds_read_b128 v[240:243], v165 offset:55296
	ds_read_b128 v[244:247], v165 offset:56320
	s_add_u32 s100, s80, s60
	s_addc_u32 s101, s81, s61
	global_load_lds_dwordx4 v132, s[100:101]
	s_add_i32 m0, s9, 0x2000
	s_add_u32 s10, s80, 0x20080
	s_addc_u32 s11, s81, 0
	s_add_i32 s9, s12, s0
	global_load_lds_dwordx4 v136, s[100:101]
	s_mov_b32 m0, s9
	s_nop 0
	global_load_lds_dwordx4 v132, s[10:11]
	s_add_i32 m0, s9, 0x2000
	s_nop 0
	global_load_lds_dwordx4 v136, s[10:11]
	s_mov_b32 m0, s66
	s_add_u32 s100, s84, s60
	s_addc_u32 s101, s85, s61
	global_load_lds_dwordx4 v130, s[100:101]
	s_mov_b32 m0, s67
	s_nop 0
	global_load_lds_dwordx4 v134, s[100:101]
	s_waitcnt vmcnt(8)
	s_waitcnt lgkmcnt(0)
	s_barrier
	v_mfma_f32_16x16x32_bf16 v[62:65], v[148:151], v[182:185], v[62:65]
	v_mfma_f32_16x16x32_bf16 v[58:61], v[156:159], v[182:185], v[58:61]
	v_mfma_f32_16x16x32_bf16 v[54:57], v[148:151], v[210:213], v[54:57]
	v_mfma_f32_16x16x32_bf16 v[50:53], v[156:159], v[210:213], v[50:53]
	v_mfma_f32_16x16x32_bf16 v[46:49], v[148:151], v[218:221], v[46:49]
	v_mfma_f32_16x16x32_bf16 v[42:45], v[156:159], v[218:221], v[42:45]
	v_mfma_f32_16x16x32_bf16 v[38:41], v[148:151], v[240:243], v[38:41]
	v_mfma_f32_16x16x32_bf16 v[34:37], v[156:159], v[240:243], v[34:37]
	v_mfma_f32_16x16x32_bf16 v[62:65], v[152:155], v[206:209], v[62:65]
	v_mfma_f32_16x16x32_bf16 v[58:61], v[160:163], v[206:209], v[58:61]
	v_mfma_f32_16x16x32_bf16 v[54:57], v[152:155], v[214:217], v[54:57]
	v_mfma_f32_16x16x32_bf16 v[50:53], v[160:163], v[214:217], v[50:53]
	v_mfma_f32_16x16x32_bf16 v[46:49], v[152:155], v[236:239], v[46:49]
	v_mfma_f32_16x16x32_bf16 v[42:45], v[160:163], v[236:239], v[42:45]
	v_mfma_f32_16x16x32_bf16 v[38:41], v[152:155], v[244:247], v[38:41]
	v_mfma_f32_16x16x32_bf16 v[34:37], v[160:163], v[244:247], v[34:37]
	v_mfma_f32_16x16x32_bf16 v[30:33], v[166:169], v[182:185], v[30:33]
	v_mfma_f32_16x16x32_bf16 v[26:29], v[174:177], v[182:185], v[26:29]
	v_mfma_f32_16x16x32_bf16 v[22:25], v[166:169], v[210:213], v[22:25]
	v_mfma_f32_16x16x32_bf16 v[18:21], v[174:177], v[210:213], v[18:21]
	v_mfma_f32_16x16x32_bf16 v[14:17], v[166:169], v[218:221], v[14:17]
	v_mfma_f32_16x16x32_bf16 v[10:13], v[174:177], v[218:221], v[10:13]
	v_mfma_f32_16x16x32_bf16 v[6:9], v[166:169], v[240:243], v[6:9]
	v_mfma_f32_16x16x32_bf16 v[2:5], v[174:177], v[240:243], v[2:5]
	v_mfma_f32_16x16x32_bf16 v[30:33], v[170:173], v[206:209], v[30:33]
	v_mfma_f32_16x16x32_bf16 v[26:29], v[178:181], v[206:209], v[26:29]
	v_mfma_f32_16x16x32_bf16 v[22:25], v[170:173], v[214:217], v[22:25]
	v_mfma_f32_16x16x32_bf16 v[18:21], v[178:181], v[214:217], v[18:21]
	v_mfma_f32_16x16x32_bf16 v[14:17], v[170:173], v[236:239], v[14:17]
	v_mfma_f32_16x16x32_bf16 v[10:13], v[178:181], v[236:239], v[10:13]
	v_mfma_f32_16x16x32_bf16 v[6:9], v[170:173], v[244:247], v[6:9]
	v_mfma_f32_16x16x32_bf16 v[2:5], v[178:181], v[244:247], v[2:5]
	s_barrier
	s_add_i32 s8, s8, 2
	s_add_u32 s46, s46, 0x100
	s_addc_u32 s47, s47, 0
	s_cmp_gt_u32 s8, 29

; #define PG8_STAGE(bufoff, gbase, voff) do { _Pragma("unroll") for (int _i = 0; _i < 2; ++_i) \
;         __builtin_amdgcn_global_load_lds((const unsigned*)((const char*)(gbase) + (voff)[_i]), (PG8_LAS unsigned*)(lds + (bufoff) + ldsw + _i * 8192), 16, 0, 0); } while (0)
; #define PG8_LDA(dst, b, h) do { _Pragma("unroll") for (int m = 0; m < 4; ++m) _Pragma("unroll") for (int k = 0; k < 2; ++k) dst[m][k] = *(const PG8_LAS bf16x8*)(lds + PG8_SA(b, h) + aoff + m * 2048 + k * 1024); } while (0)
; #define PG8_LDB(dst, b, h) do { _Pragma("unroll") for (int n = 0; n < 2; ++n) _Pragma("unroll") for (int k = 0; k < 2; ++k) dst[n][k] = *(const PG8_LAS bf16x8*)(lds + PG8_SB(b, h) + boff + n * 2048 + k * 1024); } while (0)
; template <class Epi, class Sched, bool ALIGN_EPI = false, bool SP2 = false>
; __device__ __forceinline__ void gemm_phase(PG8_LAS unsigned char* lds, const Gemm g, const Sched& S, const Epi& E) {
;     ...
;         const bool has_next = S.next(ui + 1, nxt);
;         const char* nA = has_next ? (const char*)g.A + (size_t)nxt.pm * tstep : cA; const char* nB = has_next ? (const char*)g.Bt + (size_t)nxt.pn * tstep : cB;
;         for (int t = 0; t < nt; t += 2) {
;             const bool last = (t == nt - 2);
;             const char* a1 = cA + (size_t)(t + 1) * kstep;
;             const char* a2 = last ? nA : cA + (size_t)(t + 2) * kstep; const char* b2 = last ? nB : cB + (size_t)(t + 2) * kstep;
;             const char* a3 = a2 + kstep; const char* b3 = b2 + kstep;
;             if (last && has_next) S.a_ready(nxt);
;             if constexpr (SP2) {
;             PG8_LDB(B0, 0, 0); PG8_LDB(B1, 0, 1); PG8_SCHED; PG8_LDA(At, 0, 0); PG8_STAGE(PG8_SA(1, 1), a1 + hstep, voffA);
;             PG8_WAIT_V(8); PG8_WAIT_L(0); PG8_BAR; PG8_MMA(0, 0, At, B0); PG8_MMA(0, 1, At, B1); PG8_BAR; PG8_SCHED;
;             PG8_LDA(At, 0, 1); PG8_STAGE(PG8_SB(0, 0), b2, voffB); PG8_STAGE(PG8_SB(0, 1), b2 + hstepB, voffB); PG8_STAGE(PG8_SA(0, 0), a2, voffA);
;             PG8_WAIT_V(8); PG8_WAIT_L(0); PG8_BAR; PG8_MMA(1, 0, At, B0); PG8_MMA(1, 1, At, B1); PG8_BAR; PG8_SCHED;
;     ...
; #pragma unroll
;         for (int a = 0; a < 2; ++a)
; #pragma unroll
;             for (int b = 0; b < 2; ++b)
; #pragma unroll
;                 for (int m = 0; m < 4; ++m)
; #pragma unroll
;                     for (int n = 0; n < 2; ++n) acc[a][b][m][n] = (f32x4){0.f, 0.f, 0.f, 0.f};
.LBB0_926:
	s_ashr_i32 s73, s72, 31
	s_lshl_b64 s[4:5], s[72:73], 20
	v_readlane_b32 s6, v249, 9
	v_readlane_b32 s7, v249, 10
	s_add_u32 s76, s6, s4
	s_addc_u32 s77, s7, s5
	s_and_b64 s[4:5], s[92:93], exec
	s_cselect_b32 s36, s77, s39
	s_cselect_b32 s37, s76, s38
	s_ashr_i32 s69, s68, 31
	s_lshl_b64 s[4:5], s[68:69], 20
	v_readlane_b32 s6, v249, 17
	v_readlane_b32 s7, v249, 18
	s_add_u32 s80, s6, s4
	s_addc_u32 s81, s7, s5
	s_and_b64 s[4:5], s[92:93], exec
	s_cselect_b32 s4, s81, s47
	s_cselect_b32 s5, s80, s46
	s_add_u32 s38, s38, 0x80080
	s_addc_u32 s39, s39, 0
	s_add_u32 s6, s46, 0x100
	v_mov_b32_e32 v2, 0
	s_addc_u32 s7, s47, 0
	s_mov_b32 s8, -2
	v_mov_b32_e32 v3, v2
	v_mov_b32_e32 v4, v2
	v_mov_b32_e32 v5, v2
	v_mov_b32_e32 v6, v2
	v_mov_b32_e32 v7, v2
	v_mov_b32_e32 v8, v2
	v_mov_b32_e32 v9, v2
	v_mov_b32_e32 v18, v2
	v_mov_b32_e32 v19, v2
	v_mov_b32_e32 v20, v2
	v_mov_b32_e32 v21, v2
	v_mov_b32_e32 v22, v2
	v_mov_b32_e32 v23, v2
	v_mov_b32_e32 v24, v2
	v_mov_b32_e32 v25, v2
	v_mov_b32_e32 v34, v2
	s_waitcnt lgkmcnt(0)
	v_add_u32_e32 v186, 0x10000, v193
	v_add_u32_e32 v187, 0x14000, v193
	v_add_u32_e32 v198, 0x18000, v193
	v_add_u32_e32 v199, 0x1c000, v193
	s_add_u32 s9, s38, 0xfff80080
	s_addc_u32 s10, s39, -1
	s_add_i32 s11, 0, 0x10000
	s_cmp_eq_u32 s8, 28
	s_cselect_b32 s95, s36, s10
	s_cselect_b32 s94, s37, s9
	s_cselect_b32 s47, s4, s7
	s_cselect_b32 s46, s5, s6
	s_add_i32 s9, 0, 0x14000
	ds_read_b128 v[66:69], v186
	ds_read_b128 v[70:73], v186 offset:1024
	ds_read_b128 v[78:81], v186 offset:2048
	ds_read_b128 v[86:89], v186 offset:3072
	ds_read_b128 v[146:149], v187
	ds_read_b128 v[150:153], v187 offset:1024
	ds_read_b128 v[154:157], v187 offset:2048
	ds_read_b128 v[158:161], v187 offset:3072
	s_add_i32 m0, s66, 0xc000
	ds_read_b128 v[162:165], v236
	ds_read_b128 v[166:169], v236 offset:1024
	ds_read_b128 v[170:173], v236 offset:2048
	ds_read_b128 v[174:177], v236 offset:3072
	ds_read_b128 v[178:181], v236 offset:4096
	ds_read_b128 v[182:185], v236 offset:5120
	ds_read_b128 v[216:219], v236 offset:6144
	ds_read_b128 v[220:223], v236 offset:7168
	global_load_lds_dwordx4 v212, s[38:39]
	s_add_i32 m0, s66, 0xe000
	s_nop 0
	global_load_lds_dwordx4 v214, s[38:39]
	s_waitcnt vmcnt(8)
	s_waitcnt lgkmcnt(0)
	s_barrier
	v_mfma_f32_16x16x32_bf16 v[142:145], v[66:69], v[162:165], 0
	v_mfma_f32_16x16x32_bf16 v[138:141], v[78:81], v[162:165], 0
	v_mfma_f32_16x16x32_bf16 v[126:129], v[66:69], v[170:173], 0
	v_mfma_f32_16x16x32_bf16 v[122:125], v[78:81], v[170:173], 0
	v_mfma_f32_16x16x32_bf16 v[110:113], v[66:69], v[178:181], 0
	v_mfma_f32_16x16x32_bf16 v[106:109], v[78:81], v[178:181], 0
	v_mfma_f32_16x16x32_bf16 v[94:97], v[66:69], v[216:219], 0
	v_mfma_f32_16x16x32_bf16 v[90:93], v[78:81], v[216:219], 0
	v_mfma_f32_16x16x32_bf16 v[142:145], v[70:73], v[166:169], v[142:145]
	v_mfma_f32_16x16x32_bf16 v[138:141], v[86:89], v[166:169], v[138:141]
	v_mfma_f32_16x16x32_bf16 v[126:129], v[70:73], v[174:177], v[126:129]
	v_mfma_f32_16x16x32_bf16 v[122:125], v[86:89], v[174:177], v[122:125]
	v_mfma_f32_16x16x32_bf16 v[110:113], v[70:73], v[182:185], v[110:113]
	v_mfma_f32_16x16x32_bf16 v[106:109], v[86:89], v[182:185], v[106:109]
	v_mfma_f32_16x16x32_bf16 v[94:97], v[70:73], v[220:223], v[94:97]
	v_mfma_f32_16x16x32_bf16 v[90:93], v[86:89], v[220:223], v[90:93]
	v_mfma_f32_16x16x32_bf16 v[134:137], v[146:149], v[162:165], 0
	v_mfma_f32_16x16x32_bf16 v[130:133], v[154:157], v[162:165], 0
	v_mfma_f32_16x16x32_bf16 v[118:121], v[146:149], v[170:173], 0
	v_mfma_f32_16x16x32_bf16 v[114:117], v[154:157], v[170:173], 0
	v_mfma_f32_16x16x32_bf16 v[102:105], v[146:149], v[178:181], 0
	v_mfma_f32_16x16x32_bf16 v[98:101], v[154:157], v[178:181], 0
	v_mfma_f32_16x16x32_bf16 v[82:85], v[146:149], v[216:219], 0
	v_mfma_f32_16x16x32_bf16 v[74:77], v[154:157], v[216:219], 0
	v_mfma_f32_16x16x32_bf16 v[134:137], v[150:153], v[166:169], v[134:137]
	v_mfma_f32_16x16x32_bf16 v[130:133], v[158:161], v[166:169], v[130:133]
	v_mfma_f32_16x16x32_bf16 v[118:121], v[150:153], v[174:177], v[118:121]
	v_mfma_f32_16x16x32_bf16 v[114:117], v[158:161], v[174:177], v[114:117]
	v_mfma_f32_16x16x32_bf16 v[102:105], v[150:153], v[182:185], v[102:105]
	v_mfma_f32_16x16x32_bf16 v[98:101], v[158:161], v[182:185], v[98:101]
	v_mfma_f32_16x16x32_bf16 v[82:85], v[150:153], v[220:223], v[82:85]
	v_mfma_f32_16x16x32_bf16 v[74:77], v[158:161], v[220:223], v[74:77]
	s_barrier
	s_add_i32 s10, s11, s25
	s_mov_b32 m0, s10
	ds_read_b128 v[162:165], v236 offset:16384
	ds_read_b128 v[166:169], v236 offset:17408
	ds_read_b128 v[170:173], v236 offset:18432
	ds_read_b128 v[174:177], v236 offset:19456
	ds_read_b128 v[178:181], v236 offset:20480
	ds_read_b128 v[182:185], v236 offset:21504
	ds_read_b128 v[216:219], v236 offset:22528
	ds_read_b128 v[220:223], v236 offset:23552
	global_load_lds_dwordx4 v190, s[46:47]
	s_add_i32 m0, s10, 0x2000
	s_add_u32 s10, s46, 0x20000
	s_addc_u32 s11, s47, 0
	s_add_i32 s9, s9, s25
	global_load_lds_dwordx4 v206, s[46:47]
	s_mov_b32 m0, s9
	s_nop 0
	global_load_lds_dwordx4 v190, s[10:11]
	s_add_i32 m0, s9, 0x2000
	s_nop 0
	global_load_lds_dwordx4 v206, s[10:11]
	s_mov_b32 m0, s66
	s_nop 0
	global_load_lds_dwordx4 v210, s[94:95]
	s_mov_b32 m0, s67
	s_nop 0
	global_load_lds_dwordx4 v208, s[94:95]
	s_waitcnt vmcnt(8)
	s_waitcnt lgkmcnt(0)
	s_barrier
; #define PG8_STAGE(bufoff, gbase, voff) do { _Pragma("unroll") for (int _i = 0; _i < 2; ++_i) \
;         __builtin_amdgcn_global_load_lds((const unsigned*)((const char*)(gbase) + (voff)[_i]), (PG8_LAS unsigned*)(lds + (bufoff) + ldsw + _i * 8192), 16, 0, 0); } while (0)
; #define PG8_LDA(dst, b, h) do { _Pragma("unroll") for (int m = 0; m < 4; ++m) _Pragma("unroll") for (int k = 0; k < 2; ++k) dst[m][k] = *(const PG8_LAS bf16x8*)(lds + PG8_SA(b, h) + aoff + m * 2048 + k * 1024); } while (0)
; #define PG8_LDB(dst, b, h) do { _Pragma("unroll") for (int n = 0; n < 2; ++n) _Pragma("unroll") for (int k = 0; k < 2; ++k) dst[n][k] = *(const PG8_LAS bf16x8*)(lds + PG8_SB(b, h) + boff + n * 2048 + k * 1024); } while (0)
; #define PG8_MMA(ai, bj, At, Bt) do { __builtin_amdgcn_s_setprio(1); _Pragma("unroll") for (int m = 0; m < 4; ++m) _Pragma("unroll") for (int n = 0; n < 2; ++n) _Pragma("unroll") for (int k = 0; k < 2; ++k) \
;         acc[ai][bj][m][n] = __builtin_amdgcn_mfma_f32_16x16x32_bf16(Bt[n][k], At[m][k], acc[ai][bj][m][n], 0, 0, 0); __builtin_amdgcn_s_setprio(0); } while (0)
; #define PG8_WAIT_V(n) asm volatile("s_waitcnt vmcnt(" #n ")" ::: "memory")
; #define PG8_WAIT_L(n) asm volatile("s_waitcnt lgkmcnt(" #n ")" ::: "memory")
; #define PG8_BAR __builtin_amdgcn_s_barrier()
; #define PG8_SCHED __builtin_amdgcn_sched_barrier(0)
; template <class Epi, class Sched, bool ALIGN_EPI = false, bool SP2 = false>
; __device__ __forceinline__ void gemm_phase(PG8_LAS unsigned char* lds, const Gemm g, const Sched& S, const Epi& E) {
;     ...
;             PG8_WAIT_V(8); PG8_WAIT_L(0); PG8_BAR; PG8_MMA(1, 0, At, B0); PG8_MMA(1, 1, At, B1); PG8_BAR; PG8_SCHED;
;             PG8_LDB(B0, 1, 0); PG8_LDB(B1, 1, 1); PG8_SCHED; PG8_LDA(At, 1, 0); PG8_STAGE(PG8_SA(0, 1), a2 + hstep, voffA);
;             PG8_WAIT_V(8); PG8_WAIT_L(0); PG8_BAR; PG8_MMA(0, 0, At, B0); PG8_MMA(0, 1, At, B1); PG8_BAR; PG8_SCHED;
	v_mfma_f32_16x16x32_bf16 v[62:65], v[66:69], v[162:165], 0
	v_mfma_f32_16x16x32_bf16 v[58:61], v[78:81], v[162:165], 0
	v_mfma_f32_16x16x32_bf16 v[46:49], v[66:69], v[170:173], 0
	v_mfma_f32_16x16x32_bf16 v[42:45], v[78:81], v[170:173], 0
	v_mfma_f32_16x16x32_bf16 v[30:33], v[66:69], v[178:181], 0
	v_mfma_f32_16x16x32_bf16 v[26:29], v[78:81], v[178:181], 0
	v_mfma_f32_16x16x32_bf16 v[14:17], v[66:69], v[216:219], 0
	v_mfma_f32_16x16x32_bf16 v[10:13], v[78:81], v[216:219], 0
	v_mfma_f32_16x16x32_bf16 v[62:65], v[70:73], v[166:169], v[62:65]
	v_mfma_f32_16x16x32_bf16 v[58:61], v[86:89], v[166:169], v[58:61]
	v_mfma_f32_16x16x32_bf16 v[46:49], v[70:73], v[174:177], v[46:49]
	v_mfma_f32_16x16x32_bf16 v[42:45], v[86:89], v[174:177], v[42:45]
	v_mfma_f32_16x16x32_bf16 v[30:33], v[70:73], v[182:185], v[30:33]
	v_mfma_f32_16x16x32_bf16 v[26:29], v[86:89], v[182:185], v[26:29]
	v_mfma_f32_16x16x32_bf16 v[14:17], v[70:73], v[220:223], v[14:17]
	v_mfma_f32_16x16x32_bf16 v[10:13], v[86:89], v[220:223], v[10:13]
	v_mfma_f32_16x16x32_bf16 v[54:57], v[146:149], v[162:165], 0
	v_mfma_f32_16x16x32_bf16 v[50:53], v[154:157], v[162:165], 0
	v_mfma_f32_16x16x32_bf16 v[38:41], v[146:149], v[170:173], 0
	v_mfma_f32_16x16x32_bf16 v[34:37], v[154:157], v[170:173], 0
	v_mfma_f32_16x16x32_bf16 v[22:25], v[146:149], v[178:181], 0
	v_mfma_f32_16x16x32_bf16 v[18:21], v[154:157], v[178:181], 0
	v_mfma_f32_16x16x32_bf16 v[6:9], v[146:149], v[216:219], 0
	v_mfma_f32_16x16x32_bf16 v[2:5], v[154:157], v[216:219], 0
	v_mfma_f32_16x16x32_bf16 v[54:57], v[150:153], v[166:169], v[54:57]
	v_mfma_f32_16x16x32_bf16 v[50:53], v[158:161], v[166:169], v[50:53]
	v_mfma_f32_16x16x32_bf16 v[38:41], v[150:153], v[174:177], v[38:41]
	v_mfma_f32_16x16x32_bf16 v[34:37], v[158:161], v[174:177], v[34:37]
	v_mfma_f32_16x16x32_bf16 v[22:25], v[150:153], v[182:185], v[22:25]
	v_mfma_f32_16x16x32_bf16 v[18:21], v[158:161], v[182:185], v[18:21]
	v_mfma_f32_16x16x32_bf16 v[6:9], v[150:153], v[220:223], v[6:9]
	v_mfma_f32_16x16x32_bf16 v[2:5], v[158:161], v[220:223], v[2:5]
	s_barrier
	s_add_i32 s9, 0, 0x18000
	s_add_i32 s12, 0, 0x1c000
	ds_read_b128 v[66:69], v198
	ds_read_b128 v[70:73], v198 offset:1024
	ds_read_b128 v[78:81], v198 offset:2048
	ds_read_b128 v[86:89], v198 offset:3072
	ds_read_b128 v[146:149], v199
	ds_read_b128 v[150:153], v199 offset:1024
	ds_read_b128 v[154:157], v199 offset:2048
	ds_read_b128 v[158:161], v199 offset:3072
	s_add_u32 s10, s94, 0x80000
	s_addc_u32 s11, s95, 0
	s_mov_b32 m0, s59
	ds_read_b128 v[162:165], v236 offset:32768
	ds_read_b128 v[166:169], v236 offset:33792
	ds_read_b128 v[170:173], v236 offset:34816
	ds_read_b128 v[174:177], v236 offset:35840
	ds_read_b128 v[178:181], v236 offset:36864
	ds_read_b128 v[182:185], v236 offset:37888
	ds_read_b128 v[216:219], v236 offset:38912
	ds_read_b128 v[220:223], v236 offset:39936
	global_load_lds_dwordx4 v210, s[10:11]
	s_mov_b32 m0, s74
	s_nop 0
	global_load_lds_dwordx4 v208, s[10:11]
	s_waitcnt vmcnt(8)
	s_waitcnt lgkmcnt(0)
	s_barrier
	v_mfma_f32_16x16x32_bf16 v[142:145], v[66:69], v[162:165], v[142:145]
	v_mfma_f32_16x16x32_bf16 v[138:141], v[78:81], v[162:165], v[138:141]
	v_mfma_f32_16x16x32_bf16 v[126:129], v[66:69], v[170:173], v[126:129]
	v_mfma_f32_16x16x32_bf16 v[122:125], v[78:81], v[170:173], v[122:125]
	v_mfma_f32_16x16x32_bf16 v[110:113], v[66:69], v[178:181], v[110:113]
	v_mfma_f32_16x16x32_bf16 v[106:109], v[78:81], v[178:181], v[106:109]
	v_mfma_f32_16x16x32_bf16 v[94:97], v[66:69], v[216:219], v[94:97]
	v_mfma_f32_16x16x32_bf16 v[90:93], v[78:81], v[216:219], v[90:93]
	v_mfma_f32_16x16x32_bf16 v[142:145], v[70:73], v[166:169], v[142:145]
	v_mfma_f32_16x16x32_bf16 v[138:141], v[86:89], v[166:169], v[138:141]
	v_mfma_f32_16x16x32_bf16 v[126:129], v[70:73], v[174:177], v[126:129]
	v_mfma_f32_16x16x32_bf16 v[122:125], v[86:89], v[174:177], v[122:125]
	v_mfma_f32_16x16x32_bf16 v[110:113], v[70:73], v[182:185], v[110:113]
	v_mfma_f32_16x16x32_bf16 v[106:109], v[86:89], v[182:185], v[106:109]
	v_mfma_f32_16x16x32_bf16 v[94:97], v[70:73], v[220:223], v[94:97]
	v_mfma_f32_16x16x32_bf16 v[90:93], v[86:89], v[220:223], v[90:93]
	v_mfma_f32_16x16x32_bf16 v[134:137], v[146:149], v[162:165], v[134:137]
	v_mfma_f32_16x16x32_bf16 v[130:133], v[154:157], v[162:165], v[130:133]
	v_mfma_f32_16x16x32_bf16 v[118:121], v[146:149], v[170:173], v[118:121]
	v_mfma_f32_16x16x32_bf16 v[114:117], v[154:157], v[170:173], v[114:117]
	v_mfma_f32_16x16x32_bf16 v[102:105], v[146:149], v[178:181], v[102:105]
	v_mfma_f32_16x16x32_bf16 v[98:101], v[154:157], v[178:181], v[98:101]
	v_mfma_f32_16x16x32_bf16 v[82:85], v[146:149], v[216:219], v[82:85]
	v_mfma_f32_16x16x32_bf16 v[74:77], v[154:157], v[216:219], v[74:77]
	v_mfma_f32_16x16x32_bf16 v[134:137], v[150:153], v[166:169], v[134:137]
	v_mfma_f32_16x16x32_bf16 v[130:133], v[158:161], v[166:169], v[130:133]
	v_mfma_f32_16x16x32_bf16 v[118:121], v[150:153], v[174:177], v[118:121]
	v_mfma_f32_16x16x32_bf16 v[114:117], v[158:161], v[174:177], v[114:117]
	v_mfma_f32_16x16x32_bf16 v[102:105], v[150:153], v[182:185], v[102:105]
	v_mfma_f32_16x16x32_bf16 v[98:101], v[158:161], v[182:185], v[98:101]
	v_mfma_f32_16x16x32_bf16 v[82:85], v[150:153], v[220:223], v[82:85]
	v_mfma_f32_16x16x32_bf16 v[74:77], v[158:161], v[220:223], v[74:77]
	s_barrier
; #define PG8_STAGE(bufoff, gbase, voff) do { _Pragma("unroll") for (int _i = 0; _i < 2; ++_i) \
;         __builtin_amdgcn_global_load_lds((const unsigned*)((const char*)(gbase) + (voff)[_i]), (PG8_LAS unsigned*)(lds + (bufoff) + ldsw + _i * 8192), 16, 0, 0); } while (0)
; #define PG8_LDA(dst, b, h) do { _Pragma("unroll") for (int m = 0; m < 4; ++m) _Pragma("unroll") for (int k = 0; k < 2; ++k) dst[m][k] = *(const PG8_LAS bf16x8*)(lds + PG8_SA(b, h) + aoff + m * 2048 + k * 1024); } while (0)
; #define PG8_MMA(ai, bj, At, Bt) do { __builtin_amdgcn_s_setprio(1); _Pragma("unroll") for (int m = 0; m < 4; ++m) _Pragma("unroll") for (int n = 0; n < 2; ++n) _Pragma("unroll") for (int k = 0; k < 2; ++k) \
;         acc[ai][bj][m][n] = __builtin_amdgcn_mfma_f32_16x16x32_bf16(Bt[n][k], At[m][k], acc[ai][bj][m][n], 0, 0, 0); __builtin_amdgcn_s_setprio(0); } while (0)
; #define PG8_WAIT_V(n) asm volatile("s_waitcnt vmcnt(" #n ")" ::: "memory")
; #define PG8_WAIT_L(n) asm volatile("s_waitcnt lgkmcnt(" #n ")" ::: "memory")
; #define PG8_BAR __builtin_amdgcn_s_barrier()
; #define PG8_SCHED __builtin_amdgcn_sched_barrier(0)
; template <class Epi, class Sched, bool ALIGN_EPI = false, bool SP2 = false>
; __device__ __forceinline__ void gemm_phase(PG8_LAS unsigned char* lds, const Gemm g, const Sched& S, const Epi& E) {
;     ...
;             PG8_LDA(At, 1, 1); PG8_STAGE(PG8_SB(1, 0), b3, voffB); PG8_STAGE(PG8_SB(1, 1), b3 + hstepB, voffB); PG8_STAGE(PG8_SA(1, 0), a3, voffA);
;             PG8_WAIT_V(8); PG8_WAIT_L(0); PG8_BAR; PG8_MMA(1, 0, At, B0); PG8_MMA(1, 1, At, B1); PG8_BAR; PG8_SCHED;
	s_add_i32 s9, s9, s25
	s_mov_b32 m0, s9
	ds_read_b128 v[162:165], v236 offset:49152
	ds_read_b128 v[166:169], v236 offset:50176
	ds_read_b128 v[170:173], v236 offset:51200
	ds_read_b128 v[174:177], v236 offset:52224
	ds_read_b128 v[178:181], v236 offset:53248
	ds_read_b128 v[182:185], v236 offset:54272
	ds_read_b128 v[216:219], v236 offset:55296
	ds_read_b128 v[220:223], v236 offset:56320
	s_add_u32 s100, s46, s60
	s_addc_u32 s101, s47, s61
	global_load_lds_dwordx4 v190, s[100:101]
	s_add_i32 m0, s9, 0x2000
	s_add_u32 s10, s46, 0x20080
	s_addc_u32 s11, s47, 0
	s_add_i32 s9, s12, s25
	global_load_lds_dwordx4 v206, s[100:101]
	s_mov_b32 m0, s9
	s_nop 0
	global_load_lds_dwordx4 v190, s[10:11]
	s_add_i32 m0, s9, 0x2000
	s_nop 0
	global_load_lds_dwordx4 v206, s[10:11]
	s_mov_b32 m0, s75
	s_add_u32 s100, s94, s60
	s_addc_u32 s101, s95, s61
	global_load_lds_dwordx4 v210, s[100:101]
	s_mov_b32 m0, s0
	s_nop 0
	global_load_lds_dwordx4 v208, s[100:101]
	s_waitcnt vmcnt(8)
	s_waitcnt lgkmcnt(0)
	s_barrier
	v_mfma_f32_16x16x32_bf16 v[62:65], v[66:69], v[162:165], v[62:65]
	v_mfma_f32_16x16x32_bf16 v[58:61], v[78:81], v[162:165], v[58:61]
	v_mfma_f32_16x16x32_bf16 v[46:49], v[66:69], v[170:173], v[46:49]
	v_mfma_f32_16x16x32_bf16 v[42:45], v[78:81], v[170:173], v[42:45]
	v_mfma_f32_16x16x32_bf16 v[30:33], v[66:69], v[178:181], v[30:33]
	v_mfma_f32_16x16x32_bf16 v[26:29], v[78:81], v[178:181], v[26:29]
	v_mfma_f32_16x16x32_bf16 v[14:17], v[66:69], v[216:219], v[14:17]
	v_mfma_f32_16x16x32_bf16 v[10:13], v[78:81], v[216:219], v[10:13]
	v_mfma_f32_16x16x32_bf16 v[62:65], v[70:73], v[166:169], v[62:65]
	v_mfma_f32_16x16x32_bf16 v[58:61], v[86:89], v[166:169], v[58:61]
	v_mfma_f32_16x16x32_bf16 v[46:49], v[70:73], v[174:177], v[46:49]
	v_mfma_f32_16x16x32_bf16 v[42:45], v[86:89], v[174:177], v[42:45]
	v_mfma_f32_16x16x32_bf16 v[30:33], v[70:73], v[182:185], v[30:33]
	v_mfma_f32_16x16x32_bf16 v[26:29], v[86:89], v[182:185], v[26:29]
	v_mfma_f32_16x16x32_bf16 v[14:17], v[70:73], v[220:223], v[14:17]
	v_mfma_f32_16x16x32_bf16 v[10:13], v[86:89], v[220:223], v[10:13]
	v_mfma_f32_16x16x32_bf16 v[54:57], v[146:149], v[162:165], v[54:57]
	v_mfma_f32_16x16x32_bf16 v[50:53], v[154:157], v[162:165], v[50:53]
	v_mfma_f32_16x16x32_bf16 v[38:41], v[146:149], v[170:173], v[38:41]
	v_mfma_f32_16x16x32_bf16 v[34:37], v[154:157], v[170:173], v[34:37]
	v_mfma_f32_16x16x32_bf16 v[22:25], v[146:149], v[178:181], v[22:25]
	v_mfma_f32_16x16x32_bf16 v[18:21], v[154:157], v[178:181], v[18:21]
	v_mfma_f32_16x16x32_bf16 v[6:9], v[146:149], v[216:219], v[6:9]
	v_mfma_f32_16x16x32_bf16 v[2:5], v[154:157], v[216:219], v[2:5]
	v_mfma_f32_16x16x32_bf16 v[54:57], v[150:153], v[166:169], v[54:57]
	v_mfma_f32_16x16x32_bf16 v[50:53], v[158:161], v[166:169], v[50:53]
	v_mfma_f32_16x16x32_bf16 v[38:41], v[150:153], v[174:177], v[38:41]
	v_mfma_f32_16x16x32_bf16 v[34:37], v[158:161], v[174:177], v[34:37]
	v_mfma_f32_16x16x32_bf16 v[22:25], v[150:153], v[182:185], v[22:25]
	v_mfma_f32_16x16x32_bf16 v[18:21], v[158:161], v[182:185], v[18:21]
	v_mfma_f32_16x16x32_bf16 v[6:9], v[150:153], v[220:223], v[6:9]
	v_mfma_f32_16x16x32_bf16 v[2:5], v[158:161], v[220:223], v[2:5]
	s_barrier
	s_add_i32 s8, s8, 2
	s_add_u32 s38, s38, 0x100
	s_addc_u32 s39, s39, 0
	s_add_u32 s6, s6, 0x100
	s_addc_u32 s7, s7, 0
	s_cmp_gt_u32 s8, 29

; #define PG8_STAGE(bufoff, gbase, voff) do { _Pragma("unroll") for (int _i = 0; _i < 2; ++_i) \
;         __builtin_amdgcn_global_load_lds((const unsigned*)((const char*)(gbase) + (voff)[_i]), (PG8_LAS unsigned*)(lds + (bufoff) + ldsw + _i * 8192), 16, 0, 0); } while (0)
; #define PG8_LDA(dst, b, h) do { _Pragma("unroll") for (int m = 0; m < 4; ++m) _Pragma("unroll") for (int k = 0; k < 2; ++k) dst[m][k] = *(const PG8_LAS bf16x8*)(lds + PG8_SA(b, h) + aoff + m * 2048 + k * 1024); } while (0)
; #define PG8_LDB(dst, b, h) do { _Pragma("unroll") for (int n = 0; n < 2; ++n) _Pragma("unroll") for (int k = 0; k < 2; ++k) dst[n][k] = *(const PG8_LAS bf16x8*)(lds + PG8_SB(b, h) + boff + n * 2048 + k * 1024); } while (0)
; #define PG8_MMA(ai, bj, At, Bt) do { __builtin_amdgcn_s_setprio(1); _Pragma("unroll") for (int m = 0; m < 4; ++m) _Pragma("unroll") for (int n = 0; n < 2; ++n) _Pragma("unroll") for (int k = 0; k < 2; ++k) \
;         acc[ai][bj][m][n] = __builtin_amdgcn_mfma_f32_16x16x32_bf16(Bt[n][k], At[m][k], acc[ai][bj][m][n], 0, 0, 0); __builtin_amdgcn_s_setprio(0); } while (0)
; #define PG8_BAR __builtin_amdgcn_s_barrier()
; template <class Epi, class Sched, bool ALIGN_EPI = false, bool SP2 = false>
; __device__ __forceinline__ void gemm_phase(PG8_LAS unsigned char* lds, const Gemm g, const Sched& S, const Epi& E) {
;     ...
;         const bool has_next = S.next(ui + 1, nxt);
;         const char* nA = has_next ? (const char*)g.A + (size_t)nxt.pm * tstep : cA; const char* nB = has_next ? (const char*)g.Bt + (size_t)nxt.pn * tstep : cB;
;         for (int t = 0; t < nt; t += 2) {
;             const bool last = (t == nt - 2);
;             const char* a1 = cA + (size_t)(t + 1) * kstep;
;             const char* a2 = last ? nA : cA + (size_t)(t + 2) * kstep; const char* b2 = last ? nB : cB + (size_t)(t + 2) * kstep;
;             const char* a3 = a2 + kstep; const char* b3 = b2 + kstep;
;             if (last && has_next) S.a_ready(nxt);
;             if constexpr (SP2) {
;             PG8_LDB(B0, 0, 0); PG8_LDB(B1, 0, 1); PG8_SCHED; PG8_LDA(At, 0, 0); PG8_STAGE(PG8_SA(1, 1), a1 + hstep, voffA);
;             PG8_WAIT_V(8); PG8_WAIT_L(0); PG8_BAR; PG8_MMA(0, 0, At, B0); PG8_MMA(0, 1, At, B1); PG8_BAR; PG8_SCHED;
;             PG8_LDA(At, 0, 1); PG8_STAGE(PG8_SB(0, 0), b2, voffB); PG8_STAGE(PG8_SB(0, 1), b2 + hstepB, voffB); PG8_STAGE(PG8_SA(0, 0), a2, voffA);
.LBB0_1070:
	s_ashr_i32 s97, s96, 31
	s_lshl_b64 s[4:5], s[96:97], 22
	s_add_u32 s26, s0, s4
	s_addc_u32 s27, s1, s5
	s_and_b64 s[4:5], s[92:93], exec
	s_cselect_b32 s97, s27, s39
	s_cselect_b32 s4, s26, s38
	s_ashr_i32 s85, s84, 31
	s_lshl_b64 s[6:7], s[84:85], 22
	s_add_u32 s94, s56, s6
	s_addc_u32 s95, s57, s7
	s_and_b64 s[6:7], s[92:93], exec
	s_cselect_b32 s5, s95, s47
	s_cselect_b32 s6, s94, s46
	s_add_u32 s38, s38, 0x200080
	s_addc_u32 s39, s39, 0
	s_add_u32 s7, s46, 0x100
	s_addc_u32 s8, s47, 0
	s_mov_b32 s9, -2
	s_waitcnt lgkmcnt(0)
	v_add_u32_e32 v186, 0x10000, v164
	v_add_u32_e32 v187, 0x14000, v164
	v_add_u32_e32 v198, 0x18000, v164
	v_add_u32_e32 v199, 0x1c000, v164
	s_add_u32 s10, s38, 0xffe00080
	s_addc_u32 s11, s39, -1
	s_add_i32 s12, 0, 0x10000
	s_cmpk_eq_i32 s9, 0x7c
	s_cselect_b32 vcc_hi, s97, s11
	s_cselect_b32 vcc_lo, s4, s10
	s_cselect_b32 s47, s5, s8
	s_cselect_b32 s46, s6, s7
	s_add_i32 s13, 0, 0x14000
	ds_read_b128 v[130:133], v186
	ds_read_b128 v[134:137], v186 offset:1024
	ds_read_b128 v[138:141], v186 offset:2048
	ds_read_b128 v[152:155], v186 offset:3072
	ds_read_b128 v[156:159], v187
	ds_read_b128 v[160:163], v187 offset:1024
	ds_read_b128 v[168:171], v187 offset:2048
	ds_read_b128 v[172:175], v187 offset:3072
	s_add_i32 m0, s74, 0xc000
	ds_read_b128 v[176:179], v166
	ds_read_b128 v[180:183], v166 offset:1024
	ds_read_b128 v[206:209], v166 offset:2048
	ds_read_b128 v[210:213], v166 offset:3072
	ds_read_b128 v[214:217], v166 offset:4096
	ds_read_b128 v[218:221], v166 offset:5120
	ds_read_b128 v[236:239], v166 offset:6144
	ds_read_b128 v[240:243], v166 offset:7168
	global_load_lds_dwordx4 v148, s[38:39]
	s_add_i32 m0, s74, 0xe000
	s_nop 0
	global_load_lds_dwordx4 v150, s[38:39]
	s_waitcnt vmcnt(8)
	s_waitcnt lgkmcnt(0)
	s_barrier
	v_mfma_f32_16x16x32_bf16 v[126:129], v[130:133], v[176:179], 0
	v_mfma_f32_16x16x32_bf16 v[122:125], v[138:141], v[176:179], 0
	v_mfma_f32_16x16x32_bf16 v[110:113], v[130:133], v[206:209], 0
	v_mfma_f32_16x16x32_bf16 v[106:109], v[138:141], v[206:209], 0
	v_mfma_f32_16x16x32_bf16 v[94:97], v[130:133], v[214:217], 0
	v_mfma_f32_16x16x32_bf16 v[90:93], v[138:141], v[214:217], 0
	v_mfma_f32_16x16x32_bf16 v[78:81], v[130:133], v[236:239], 0
	v_mfma_f32_16x16x32_bf16 v[74:77], v[138:141], v[236:239], 0
	v_mfma_f32_16x16x32_bf16 v[126:129], v[134:137], v[180:183], v[126:129]
	v_mfma_f32_16x16x32_bf16 v[122:125], v[152:155], v[180:183], v[122:125]
	v_mfma_f32_16x16x32_bf16 v[110:113], v[134:137], v[210:213], v[110:113]
	v_mfma_f32_16x16x32_bf16 v[106:109], v[152:155], v[210:213], v[106:109]
	v_mfma_f32_16x16x32_bf16 v[94:97], v[134:137], v[218:221], v[94:97]
	v_mfma_f32_16x16x32_bf16 v[90:93], v[152:155], v[218:221], v[90:93]
	v_mfma_f32_16x16x32_bf16 v[78:81], v[134:137], v[240:243], v[78:81]
	v_mfma_f32_16x16x32_bf16 v[74:77], v[152:155], v[240:243], v[74:77]
	v_mfma_f32_16x16x32_bf16 v[118:121], v[156:159], v[176:179], 0
	v_mfma_f32_16x16x32_bf16 v[114:117], v[168:171], v[176:179], 0
	v_mfma_f32_16x16x32_bf16 v[102:105], v[156:159], v[206:209], 0
	v_mfma_f32_16x16x32_bf16 v[98:101], v[168:171], v[206:209], 0
	v_mfma_f32_16x16x32_bf16 v[86:89], v[156:159], v[214:217], 0
	v_mfma_f32_16x16x32_bf16 v[82:85], v[168:171], v[214:217], 0
	v_mfma_f32_16x16x32_bf16 v[70:73], v[156:159], v[236:239], 0
	v_mfma_f32_16x16x32_bf16 v[66:69], v[168:171], v[236:239], 0
	v_mfma_f32_16x16x32_bf16 v[118:121], v[160:163], v[180:183], v[118:121]
	v_mfma_f32_16x16x32_bf16 v[114:117], v[172:175], v[180:183], v[114:117]
	v_mfma_f32_16x16x32_bf16 v[102:105], v[160:163], v[210:213], v[102:105]
	v_mfma_f32_16x16x32_bf16 v[98:101], v[172:175], v[210:213], v[98:101]
	v_mfma_f32_16x16x32_bf16 v[86:89], v[160:163], v[218:221], v[86:89]
	v_mfma_f32_16x16x32_bf16 v[82:85], v[172:175], v[218:221], v[82:85]
	v_mfma_f32_16x16x32_bf16 v[70:73], v[160:163], v[240:243], v[70:73]
	v_mfma_f32_16x16x32_bf16 v[66:69], v[172:175], v[240:243], v[66:69]
	s_barrier
	s_add_i32 s10, s12, s67
	s_mov_b32 m0, s10
	ds_read_b128 v[176:179], v166 offset:16384
	ds_read_b128 v[180:183], v166 offset:17408
	ds_read_b128 v[206:209], v166 offset:18432
	ds_read_b128 v[210:213], v166 offset:19456
	ds_read_b128 v[214:217], v166 offset:20480
	ds_read_b128 v[218:221], v166 offset:21504
	ds_read_b128 v[236:239], v166 offset:22528
	ds_read_b128 v[240:243], v166 offset:23552
	global_load_lds_dwordx4 v146, s[46:47]
	s_add_i32 m0, s10, 0x2000
	s_add_u32 s10, s46, 0x80000
	s_addc_u32 s11, s47, 0
	s_add_i32 s12, s13, s67
	global_load_lds_dwordx4 v142, s[46:47]
	s_mov_b32 m0, s12
	s_nop 0
	global_load_lds_dwordx4 v146, s[10:11]
	s_add_i32 m0, s12, 0x2000
	s_nop 0
	global_load_lds_dwordx4 v142, s[10:11]
	s_mov_b32 m0, s74
	s_nop 0
	global_load_lds_dwordx4 v190, vcc
	s_mov_b32 m0, s75
	s_nop 0
	global_load_lds_dwordx4 v144, vcc
	s_waitcnt vmcnt(8)
	s_waitcnt lgkmcnt(0)
	s_barrier
; #define PG8_STAGE(bufoff, gbase, voff) do { _Pragma("unroll") for (int _i = 0; _i < 2; ++_i) \
;         __builtin_amdgcn_global_load_lds((const unsigned*)((const char*)(gbase) + (voff)[_i]), (PG8_LAS unsigned*)(lds + (bufoff) + ldsw + _i * 8192), 16, 0, 0); } while (0)
; #define PG8_LDA(dst, b, h) do { _Pragma("unroll") for (int m = 0; m < 4; ++m) _Pragma("unroll") for (int k = 0; k < 2; ++k) dst[m][k] = *(const PG8_LAS bf16x8*)(lds + PG8_SA(b, h) + aoff + m * 2048 + k * 1024); } while (0)
; #define PG8_LDB(dst, b, h) do { _Pragma("unroll") for (int n = 0; n < 2; ++n) _Pragma("unroll") for (int k = 0; k < 2; ++k) dst[n][k] = *(const PG8_LAS bf16x8*)(lds + PG8_SB(b, h) + boff + n * 2048 + k * 1024); } while (0)
; #define PG8_MMA(ai, bj, At, Bt) do { __builtin_amdgcn_s_setprio(1); _Pragma("unroll") for (int m = 0; m < 4; ++m) _Pragma("unroll") for (int n = 0; n < 2; ++n) _Pragma("unroll") for (int k = 0; k < 2; ++k) \
;         acc[ai][bj][m][n] = __builtin_amdgcn_mfma_f32_16x16x32_bf16(Bt[n][k], At[m][k], acc[ai][bj][m][n], 0, 0, 0); __builtin_amdgcn_s_setprio(0); } while (0)
; #define PG8_WAIT_V(n) asm volatile("s_waitcnt vmcnt(" #n ")" ::: "memory")
; #define PG8_WAIT_L(n) asm volatile("s_waitcnt lgkmcnt(" #n ")" ::: "memory")
; #define PG8_BAR __builtin_amdgcn_s_barrier()
; #define PG8_SCHED __builtin_amdgcn_sched_barrier(0)
; template <class Epi, class Sched, bool ALIGN_EPI = false, bool SP2 = false>
; __device__ __forceinline__ void gemm_phase(PG8_LAS unsigned char* lds, const Gemm g, const Sched& S, const Epi& E) {
;     ...
;             PG8_WAIT_V(8); PG8_WAIT_L(0); PG8_BAR; PG8_MMA(1, 0, At, B0); PG8_MMA(1, 1, At, B1); PG8_BAR; PG8_SCHED;
;             PG8_LDB(B0, 1, 0); PG8_LDB(B1, 1, 1); PG8_SCHED; PG8_LDA(At, 1, 0); PG8_STAGE(PG8_SA(0, 1), a2 + hstep, voffA);
;             PG8_WAIT_V(8); PG8_WAIT_L(0); PG8_BAR; PG8_MMA(0, 0, At, B0); PG8_MMA(0, 1, At, B1); PG8_BAR; PG8_SCHED;
	v_mfma_f32_16x16x32_bf16 v[62:65], v[130:133], v[176:179], 0
	v_mfma_f32_16x16x32_bf16 v[58:61], v[138:141], v[176:179], 0
	v_mfma_f32_16x16x32_bf16 v[46:49], v[130:133], v[206:209], 0
	v_mfma_f32_16x16x32_bf16 v[42:45], v[138:141], v[206:209], 0
	v_mfma_f32_16x16x32_bf16 v[30:33], v[130:133], v[214:217], 0
	v_mfma_f32_16x16x32_bf16 v[26:29], v[138:141], v[214:217], 0
	v_mfma_f32_16x16x32_bf16 v[14:17], v[130:133], v[236:239], 0
	v_mfma_f32_16x16x32_bf16 v[10:13], v[138:141], v[236:239], 0
	v_mfma_f32_16x16x32_bf16 v[62:65], v[134:137], v[180:183], v[62:65]
	v_mfma_f32_16x16x32_bf16 v[58:61], v[152:155], v[180:183], v[58:61]
	v_mfma_f32_16x16x32_bf16 v[46:49], v[134:137], v[210:213], v[46:49]
	v_mfma_f32_16x16x32_bf16 v[42:45], v[152:155], v[210:213], v[42:45]
	v_mfma_f32_16x16x32_bf16 v[30:33], v[134:137], v[218:221], v[30:33]
	v_mfma_f32_16x16x32_bf16 v[26:29], v[152:155], v[218:221], v[26:29]
	v_mfma_f32_16x16x32_bf16 v[14:17], v[134:137], v[240:243], v[14:17]
	v_mfma_f32_16x16x32_bf16 v[10:13], v[152:155], v[240:243], v[10:13]
	v_mfma_f32_16x16x32_bf16 v[54:57], v[156:159], v[176:179], 0
	v_mfma_f32_16x16x32_bf16 v[50:53], v[168:171], v[176:179], 0
	v_mfma_f32_16x16x32_bf16 v[38:41], v[156:159], v[206:209], 0
	v_mfma_f32_16x16x32_bf16 v[34:37], v[168:171], v[206:209], 0
	v_mfma_f32_16x16x32_bf16 v[22:25], v[156:159], v[214:217], 0
	v_mfma_f32_16x16x32_bf16 v[18:21], v[168:171], v[214:217], 0
	v_mfma_f32_16x16x32_bf16 v[6:9], v[156:159], v[236:239], 0
	v_mfma_f32_16x16x32_bf16 v[2:5], v[168:171], v[236:239], 0
	v_mfma_f32_16x16x32_bf16 v[54:57], v[160:163], v[180:183], v[54:57]
	v_mfma_f32_16x16x32_bf16 v[50:53], v[172:175], v[180:183], v[50:53]
	v_mfma_f32_16x16x32_bf16 v[38:41], v[160:163], v[210:213], v[38:41]
	v_mfma_f32_16x16x32_bf16 v[34:37], v[172:175], v[210:213], v[34:37]
	v_mfma_f32_16x16x32_bf16 v[22:25], v[160:163], v[218:221], v[22:25]
	v_mfma_f32_16x16x32_bf16 v[18:21], v[172:175], v[218:221], v[18:21]
	v_mfma_f32_16x16x32_bf16 v[6:9], v[160:163], v[240:243], v[6:9]
	v_mfma_f32_16x16x32_bf16 v[2:5], v[172:175], v[240:243], v[2:5]
	s_barrier
	s_add_i32 s12, 0, 0x18000
	s_add_i32 s13, 0, 0x1c000
	ds_read_b128 v[130:133], v198
	ds_read_b128 v[134:137], v198 offset:1024
	ds_read_b128 v[138:141], v198 offset:2048
	ds_read_b128 v[152:155], v198 offset:3072
	ds_read_b128 v[156:159], v199
	ds_read_b128 v[160:163], v199 offset:1024
	ds_read_b128 v[168:171], v199 offset:2048
	ds_read_b128 v[172:175], v199 offset:3072
	s_add_u32 s10, vcc_lo, 0x200000
	s_addc_u32 s11, vcc_hi, 0
	s_mov_b32 m0, s86
	ds_read_b128 v[176:179], v166 offset:32768
	ds_read_b128 v[180:183], v166 offset:33792
	ds_read_b128 v[206:209], v166 offset:34816
	ds_read_b128 v[210:213], v166 offset:35840
	ds_read_b128 v[214:217], v166 offset:36864
	ds_read_b128 v[218:221], v166 offset:37888
	ds_read_b128 v[236:239], v166 offset:38912
	ds_read_b128 v[240:243], v166 offset:39936
	global_load_lds_dwordx4 v190, s[10:11]
	s_mov_b32 m0, s87
	s_nop 0
	global_load_lds_dwordx4 v144, s[10:11]
	s_waitcnt vmcnt(8)
	s_waitcnt lgkmcnt(0)
	s_barrier
	v_mfma_f32_16x16x32_bf16 v[126:129], v[130:133], v[176:179], v[126:129]
	v_mfma_f32_16x16x32_bf16 v[122:125], v[138:141], v[176:179], v[122:125]
	v_mfma_f32_16x16x32_bf16 v[110:113], v[130:133], v[206:209], v[110:113]
	v_mfma_f32_16x16x32_bf16 v[106:109], v[138:141], v[206:209], v[106:109]
	v_mfma_f32_16x16x32_bf16 v[94:97], v[130:133], v[214:217], v[94:97]
	v_mfma_f32_16x16x32_bf16 v[90:93], v[138:141], v[214:217], v[90:93]
	v_mfma_f32_16x16x32_bf16 v[78:81], v[130:133], v[236:239], v[78:81]
	v_mfma_f32_16x16x32_bf16 v[74:77], v[138:141], v[236:239], v[74:77]
	v_mfma_f32_16x16x32_bf16 v[126:129], v[134:137], v[180:183], v[126:129]
	v_mfma_f32_16x16x32_bf16 v[122:125], v[152:155], v[180:183], v[122:125]
	v_mfma_f32_16x16x32_bf16 v[110:113], v[134:137], v[210:213], v[110:113]
	v_mfma_f32_16x16x32_bf16 v[106:109], v[152:155], v[210:213], v[106:109]
	v_mfma_f32_16x16x32_bf16 v[94:97], v[134:137], v[218:221], v[94:97]
	v_mfma_f32_16x16x32_bf16 v[90:93], v[152:155], v[218:221], v[90:93]
	v_mfma_f32_16x16x32_bf16 v[78:81], v[134:137], v[240:243], v[78:81]
	v_mfma_f32_16x16x32_bf16 v[74:77], v[152:155], v[240:243], v[74:77]
	v_mfma_f32_16x16x32_bf16 v[118:121], v[156:159], v[176:179], v[118:121]
	v_mfma_f32_16x16x32_bf16 v[114:117], v[168:171], v[176:179], v[114:117]
	v_mfma_f32_16x16x32_bf16 v[102:105], v[156:159], v[206:209], v[102:105]
	v_mfma_f32_16x16x32_bf16 v[98:101], v[168:171], v[206:209], v[98:101]
	v_mfma_f32_16x16x32_bf16 v[86:89], v[156:159], v[214:217], v[86:89]
	v_mfma_f32_16x16x32_bf16 v[82:85], v[168:171], v[214:217], v[82:85]
	v_mfma_f32_16x16x32_bf16 v[70:73], v[156:159], v[236:239], v[70:73]
	v_mfma_f32_16x16x32_bf16 v[66:69], v[168:171], v[236:239], v[66:69]
	v_mfma_f32_16x16x32_bf16 v[118:121], v[160:163], v[180:183], v[118:121]
	v_mfma_f32_16x16x32_bf16 v[114:117], v[172:175], v[180:183], v[114:117]
	v_mfma_f32_16x16x32_bf16 v[102:105], v[160:163], v[210:213], v[102:105]
	v_mfma_f32_16x16x32_bf16 v[98:101], v[172:175], v[210:213], v[98:101]
	v_mfma_f32_16x16x32_bf16 v[86:89], v[160:163], v[218:221], v[86:89]
	v_mfma_f32_16x16x32_bf16 v[82:85], v[172:175], v[218:221], v[82:85]
	v_mfma_f32_16x16x32_bf16 v[70:73], v[160:163], v[240:243], v[70:73]
	v_mfma_f32_16x16x32_bf16 v[66:69], v[172:175], v[240:243], v[66:69]
	s_barrier
; #define PG8_STAGE(bufoff, gbase, voff) do { _Pragma("unroll") for (int _i = 0; _i < 2; ++_i) \
;         __builtin_amdgcn_global_load_lds((const unsigned*)((const char*)(gbase) + (voff)[_i]), (PG8_LAS unsigned*)(lds + (bufoff) + ldsw + _i * 8192), 16, 0, 0); } while (0)
; #define PG8_LDA(dst, b, h) do { _Pragma("unroll") for (int m = 0; m < 4; ++m) _Pragma("unroll") for (int k = 0; k < 2; ++k) dst[m][k] = *(const PG8_LAS bf16x8*)(lds + PG8_SA(b, h) + aoff + m * 2048 + k * 1024); } while (0)
; #define PG8_MMA(ai, bj, At, Bt) do { __builtin_amdgcn_s_setprio(1); _Pragma("unroll") for (int m = 0; m < 4; ++m) _Pragma("unroll") for (int n = 0; n < 2; ++n) _Pragma("unroll") for (int k = 0; k < 2; ++k) \
;         acc[ai][bj][m][n] = __builtin_amdgcn_mfma_f32_16x16x32_bf16(Bt[n][k], At[m][k], acc[ai][bj][m][n], 0, 0, 0); __builtin_amdgcn_s_setprio(0); } while (0)
; #define PG8_WAIT_V(n) asm volatile("s_waitcnt vmcnt(" #n ")" ::: "memory")
; #define PG8_WAIT_L(n) asm volatile("s_waitcnt lgkmcnt(" #n ")" ::: "memory")
; #define PG8_BAR __builtin_amdgcn_s_barrier()
; #define PG8_SCHED __builtin_amdgcn_sched_barrier(0)
; template <class Epi, class Sched, bool ALIGN_EPI = false, bool SP2 = false>
; __device__ __forceinline__ void gemm_phase(PG8_LAS unsigned char* lds, const Gemm g, const Sched& S, const Epi& E) {
;     ...
;             PG8_LDA(At, 1, 1); PG8_STAGE(PG8_SB(1, 0), b3, voffB); PG8_STAGE(PG8_SB(1, 1), b3 + hstepB, voffB); PG8_STAGE(PG8_SA(1, 0), a3, voffA);
;             PG8_WAIT_V(8); PG8_WAIT_L(0); PG8_BAR; PG8_MMA(1, 0, At, B0); PG8_MMA(1, 1, At, B1); PG8_BAR; PG8_SCHED;
	s_add_i32 s10, s12, s67
	s_mov_b32 m0, s10
	ds_read_b128 v[176:179], v166 offset:49152
	ds_read_b128 v[180:183], v166 offset:50176
	ds_read_b128 v[206:209], v166 offset:51200
	ds_read_b128 v[210:213], v166 offset:52224
	ds_read_b128 v[214:217], v166 offset:53248
	ds_read_b128 v[218:221], v166 offset:54272
	ds_read_b128 v[236:239], v166 offset:55296
	ds_read_b128 v[240:243], v166 offset:56320
	s_add_u32 s100, s46, s60
	s_addc_u32 s101, s47, s61
	global_load_lds_dwordx4 v146, s[100:101]
	s_add_i32 m0, s10, 0x2000
	s_add_u32 s10, s46, 0x80080
	s_addc_u32 s11, s47, 0
	s_add_i32 s12, s13, s67
	global_load_lds_dwordx4 v142, s[100:101]
	s_mov_b32 m0, s12
	s_nop 0
	global_load_lds_dwordx4 v146, s[10:11]
	s_add_i32 m0, s12, 0x2000
	s_nop 0
	global_load_lds_dwordx4 v142, s[10:11]
	s_mov_b32 m0, s82
	s_add_u32 s100, vcc_lo, s60
	s_addc_u32 s101, vcc_hi, s61
	global_load_lds_dwordx4 v190, s[100:101]
	s_mov_b32 m0, s42
	s_nop 0
	global_load_lds_dwordx4 v144, s[100:101]
	s_waitcnt vmcnt(8)
	s_waitcnt lgkmcnt(0)
	s_barrier
	v_mfma_f32_16x16x32_bf16 v[62:65], v[130:133], v[176:179], v[62:65]
	v_mfma_f32_16x16x32_bf16 v[58:61], v[138:141], v[176:179], v[58:61]
	v_mfma_f32_16x16x32_bf16 v[46:49], v[130:133], v[206:209], v[46:49]
	v_mfma_f32_16x16x32_bf16 v[42:45], v[138:141], v[206:209], v[42:45]
	v_mfma_f32_16x16x32_bf16 v[30:33], v[130:133], v[214:217], v[30:33]
	v_mfma_f32_16x16x32_bf16 v[26:29], v[138:141], v[214:217], v[26:29]
	v_mfma_f32_16x16x32_bf16 v[14:17], v[130:133], v[236:239], v[14:17]
	v_mfma_f32_16x16x32_bf16 v[10:13], v[138:141], v[236:239], v[10:13]
	v_mfma_f32_16x16x32_bf16 v[62:65], v[134:137], v[180:183], v[62:65]
	v_mfma_f32_16x16x32_bf16 v[58:61], v[152:155], v[180:183], v[58:61]
	v_mfma_f32_16x16x32_bf16 v[46:49], v[134:137], v[210:213], v[46:49]
	v_mfma_f32_16x16x32_bf16 v[42:45], v[152:155], v[210:213], v[42:45]
	v_mfma_f32_16x16x32_bf16 v[30:33], v[134:137], v[218:221], v[30:33]
	v_mfma_f32_16x16x32_bf16 v[26:29], v[152:155], v[218:221], v[26:29]
	v_mfma_f32_16x16x32_bf16 v[14:17], v[134:137], v[240:243], v[14:17]
	v_mfma_f32_16x16x32_bf16 v[10:13], v[152:155], v[240:243], v[10:13]
	v_mfma_f32_16x16x32_bf16 v[54:57], v[156:159], v[176:179], v[54:57]
	v_mfma_f32_16x16x32_bf16 v[50:53], v[168:171], v[176:179], v[50:53]
	v_mfma_f32_16x16x32_bf16 v[38:41], v[156:159], v[206:209], v[38:41]
	v_mfma_f32_16x16x32_bf16 v[34:37], v[168:171], v[206:209], v[34:37]
	v_mfma_f32_16x16x32_bf16 v[22:25], v[156:159], v[214:217], v[22:25]
	v_mfma_f32_16x16x32_bf16 v[18:21], v[168:171], v[214:217], v[18:21]
	v_mfma_f32_16x16x32_bf16 v[6:9], v[156:159], v[236:239], v[6:9]
	v_mfma_f32_16x16x32_bf16 v[2:5], v[168:171], v[236:239], v[2:5]
	v_mfma_f32_16x16x32_bf16 v[54:57], v[160:163], v[180:183], v[54:57]
	v_mfma_f32_16x16x32_bf16 v[50:53], v[172:175], v[180:183], v[50:53]
	v_mfma_f32_16x16x32_bf16 v[38:41], v[160:163], v[210:213], v[38:41]
	v_mfma_f32_16x16x32_bf16 v[34:37], v[172:175], v[210:213], v[34:37]
	v_mfma_f32_16x16x32_bf16 v[22:25], v[160:163], v[218:221], v[22:25]
	v_mfma_f32_16x16x32_bf16 v[18:21], v[172:175], v[218:221], v[18:21]
	v_mfma_f32_16x16x32_bf16 v[6:9], v[160:163], v[240:243], v[6:9]
	v_mfma_f32_16x16x32_bf16 v[2:5], v[172:175], v[240:243], v[2:5]
	s_barrier
	s_add_i32 s9, s9, 2
	s_add_u32 s38, s38, 0x100
	s_addc_u32 s39, s39, 0
	s_add_u32 s7, s7, 0x100
	s_addc_u32 s8, s8, 0
	s_cmpk_gt_u32 s9, 0x7d

; #define PG8_STAGE(bufoff, gbase, voff) do { _Pragma("unroll") for (int _i = 0; _i < 2; ++_i) \
;         __builtin_amdgcn_global_load_lds((const unsigned*)((const char*)(gbase) + (voff)[_i]), (PG8_LAS unsigned*)(lds + (bufoff) + ldsw + _i * 8192), 16, 0, 0); } while (0)
; #define PG8_WAIT_V(n) asm volatile("s_waitcnt vmcnt(" #n ")" ::: "memory")
; #define PG8_BAR __builtin_amdgcn_s_barrier()
; template <class Epi, class Sched, bool ALIGN_EPI = false, bool SP2 = false>
; __device__ __forceinline__ void gemm_phase(PG8_LAS unsigned char* lds, const Gemm g, const Sched& S, const Epi& E) {
;     ...
;     for (int i = 0; i < 2; ++i) { int R, C; stage_rc(tid * 16 + i * 8192, R, C); const int Rb = Epi::PERM ? (64 * (R >> 5) + perm32(R & 31)) : R;
;         voffA[i] = (unsigned)(R * K + C) * 2u; voffB[i] = (unsigned)(Rb * K + C) * 2u; }
;     const size_t kstep = (size_t)(BK * 2);
;     const size_t hstep = (size_t)HALF * K * 2;
;     const size_t hstepB = Epi::PERM ? (size_t)32 * K * 2 : hstep;
;     const size_t tstep = 2 * hstep;
;     const unsigned ldsw = (unsigned)wid * 1024u;
;     const int aoff = lds_byte(wr * 64 + fr, fq * 8), boff = lds_byte(wc * 32 + fr, fq * 8);
;     ...
;     Unit cur, nxt; int ui = 0;
;     if (!S.next(0, cur)) return;
;     if constexpr (Epi::HAS_PRE) E.pre_all(S, tid);
;     f32x4 acc[2][2][4][2];
; #pragma unroll
;     for (int a = 0; a < 2; ++a)
; #pragma unroll
;         for (int b = 0; b < 2; ++b)
; #pragma unroll
;             for (int m = 0; m < 4; ++m)
; #pragma unroll
;                 for (int n = 0; n < 2; ++n) acc[a][b][m][n] = (f32x4){0.f, 0.f, 0.f, 0.f};
;     bf16x8 At[4][2], B0[2][2], B1[2][2];
;     const char* cA = (const char*)g.A + (size_t)cur.pm * tstep; const char* cB = (const char*)g.Bt + (size_t)cur.pn * tstep;
;     S.a_ready(cur);
;     if constexpr (SP2) {
;         PG8_STAGE(PG8_SB(0, 0), cB, voffB); PG8_STAGE(PG8_SB(0, 1), cB + hstepB, voffB); PG8_STAGE(PG8_SA(0, 0), cA, voffA); PG8_STAGE(PG8_SA(0, 1), cA + hstep, voffA);
;         if (wr == 1) PG8_BAR;
;         PG8_WAIT_V(2); PG8_BAR;
;         PG8_STAGE(PG8_SB(1, 0), cB + kstep, voffB); PG8_STAGE(PG8_SA(1, 0), cA + kstep, voffA); PG8_STAGE(PG8_SB(1, 1), cB + hstepB + kstep, voffB);
;         PG8_WAIT_V(6); PG8_BAR;
.LBB0_1224:
	v_lshrrev_b32_e32 v17, 1, v26
	v_readlane_b32 s80, v252, 17
	s_lshl_b32 s6, s59, 27
	v_and_b32_e32 v17, 24, v17
	v_mov_b32_e32 v131, v191
	v_readlane_b32 s81, v252, 18
	s_and_b32 s6, s6, 0x8000000
	v_and_b32_e32 v16, 15, v26
	v_lshlrev_b32_e32 v18, 1, v17
	v_lshl_add_u64 v[12:13], s[80:81], 0, v[130:131]
	v_mov_b32_e32 v135, v191
	s_add_u32 s54, s64, s6
	v_lshl_or_b32 v1, s5, 6, v16
	v_lshl_or_b32 v18, v16, 6, v18
	v_lshlrev_b32_e32 v16, 2, v16
	v_lshl_add_u64 v[14:15], s[80:81], 0, v[134:135]
	s_addc_u32 s55, s65, 0
	s_and_b32 s4, s4, 3
	s_lshl_b32 s6, s5, 13
	v_and_b32_e32 v19, 32, v16
	s_add_i32 m0, s51, 0x18000
	v_lshl_add_u64 v[12:13], v[12:13], 0, s[60:61]
	v_bitop3_b32 v20, v18, s6, v19 bitop3:0xde
	s_lshl_b32 s6, s4, 12
	s_waitcnt vmcnt(2)
	s_barrier
	global_load_lds_dwordx4 v[12:13], off
	v_lshl_add_u64 v[12:13], v[14:15], 0, s[60:61]
	s_add_i32 m0, s51, 0x1a000
	s_add_i32 s82, s51, 0x8000
	v_bitop3_b32 v145, v18, s6, v19 bitop3:0xde
	global_load_lds_dwordx4 v[12:13], off
	v_lshl_add_u64 v[2:3], v[2:3], 0, s[60:61]
	s_mov_b32 m0, s82
	s_add_i32 s86, s51, 0xa000
	v_readlane_b32 s6, v249, 15
	global_load_lds_dwordx4 v[2:3], off
	v_lshl_add_u64 v[2:3], v[4:5], 0, s[60:61]
	s_mov_b32 m0, s86
	v_readlane_b32 s7, v249, 16
	global_load_lds_dwordx4 v[2:3], off
	s_add_i32 m0, s51, 0x1c000
	v_lshl_add_u64 v[2:3], s[6:7], 0, v[130:131]
	global_load_lds_dwordx4 v[2:3], off
	v_lshl_add_u64 v[2:3], s[6:7], 0, v[134:135]
	s_add_i32 m0, s51, 0x1e000
	s_cmpk_lt_u32 s36, 0x100
	global_load_lds_dwordx4 v[2:3], off
	v_lshlrev_b32_e32 v2, 15, v6
	v_and_b32_e32 v2, 0xffff0000, v2
	v_lshl_add_u32 v2, v7, 12, v2
	v_and_b32_e32 v3, 1, v6
	v_lshl_or_b32 v2, v3, 6, v2
	v_lshl_add_u32 v136, v8, 1, v2
	v_lshlrev_b32_e32 v2, 15, v9
	s_cselect_b64 s[62:63], -1, 0
	s_lshl_b32 s5, s5, 8
	v_and_b32_e32 v2, 0xffff0000, v2
	s_add_i32 s5, s5, 0
	v_lshl_add_u32 v2, v10, 12, v2
	v_and_b32_e32 v3, 1, v9
	s_waitcnt vmcnt(6)
	s_add_i32 s5, s5, 0x20000
	v_lshl_or_b32 v2, v3, 6, v2
	v_add_u32_e32 v147, s5, v16
	v_lshl_or_b32 v149, s4, 6, v17
	v_lshl_add_u32 v138, v11, 1, v2
	v_mov_b32_e32 v2, 0
	v_readlane_b32 s4, v249, 28
	v_mov_b32_e32 v137, v191
	v_mov_b32_e32 v139, v191
	s_mov_b32 s95, 0
	v_add_u32_e32 v151, 0, v20
	v_readlane_b32 s87, v249, 30
	s_mov_b32 s94, s4
	s_barrier
	v_readlane_b32 s5, v249, 29
	s_branch .LBB0_1226
.LBB0_1225:
	s_mov_b32 s87, s70
	s_mov_b32 s94, s72
	s_mov_b64 s[68:69], s[78:79]
	s_mov_b32 s95, s96
	s_andn2_b64 vcc, exec, s[38:39]
	s_mov_b64 s[80:81], s[76:77]
	s_cbranch_vccz .LBB0_1240

; #define PG8_STAGE(bufoff, gbase, voff) do { _Pragma("unroll") for (int _i = 0; _i < 2; ++_i) \
;         __builtin_amdgcn_global_load_lds((const unsigned*)((const char*)(gbase) + (voff)[_i]), (PG8_LAS unsigned*)(lds + (bufoff) + ldsw + _i * 8192), 16, 0, 0); } while (0)
; #define PG8_LDA(dst, b, h) do { _Pragma("unroll") for (int m = 0; m < 4; ++m) _Pragma("unroll") for (int k = 0; k < 2; ++k) dst[m][k] = *(const PG8_LAS bf16x8*)(lds + PG8_SA(b, h) + aoff + m * 2048 + k * 1024); } while (0)
; #define PG8_LDB(dst, b, h) do { _Pragma("unroll") for (int n = 0; n < 2; ++n) _Pragma("unroll") for (int k = 0; k < 2; ++k) dst[n][k] = *(const PG8_LAS bf16x8*)(lds + PG8_SB(b, h) + boff + n * 2048 + k * 1024); } while (0)
; #define PG8_MMA(ai, bj, At, Bt) do { __builtin_amdgcn_s_setprio(1); _Pragma("unroll") for (int m = 0; m < 4; ++m) _Pragma("unroll") for (int n = 0; n < 2; ++n) _Pragma("unroll") for (int k = 0; k < 2; ++k) \
;         acc[ai][bj][m][n] = __builtin_amdgcn_mfma_f32_16x16x32_bf16(Bt[n][k], At[m][k], acc[ai][bj][m][n], 0, 0, 0); __builtin_amdgcn_s_setprio(0); } while (0)
; #define PG8_BAR __builtin_amdgcn_s_barrier()
; template <class Epi, class Sched, bool ALIGN_EPI = false, bool SP2 = false>
; __device__ __forceinline__ void gemm_phase(PG8_LAS unsigned char* lds, const Gemm g, const Sched& S, const Epi& E) {
;     ...
;         const bool has_next = S.next(ui + 1, nxt);
;         const char* nA = has_next ? (const char*)g.A + (size_t)nxt.pm * tstep : cA; const char* nB = has_next ? (const char*)g.Bt + (size_t)nxt.pn * tstep : cB;
;         for (int t = 0; t < nt; t += 2) {
;             const bool last = (t == nt - 2);
;             const char* a1 = cA + (size_t)(t + 1) * kstep;
;             const char* a2 = last ? nA : cA + (size_t)(t + 2) * kstep; const char* b2 = last ? nB : cB + (size_t)(t + 2) * kstep;
;             const char* a3 = a2 + kstep; const char* b3 = b2 + kstep;
;             if (last && has_next) S.a_ready(nxt);
;             if constexpr (SP2) {
;             PG8_LDB(B0, 0, 0); PG8_LDB(B1, 0, 1); PG8_SCHED; PG8_LDA(At, 0, 0); PG8_STAGE(PG8_SA(1, 1), a1 + hstep, voffA);
;             PG8_WAIT_V(8); PG8_WAIT_L(0); PG8_BAR; PG8_MMA(0, 0, At, B0); PG8_MMA(0, 1, At, B1); PG8_BAR; PG8_SCHED;
;             PG8_LDA(At, 0, 1); PG8_STAGE(PG8_SB(0, 0), b2, voffB); PG8_STAGE(PG8_SB(0, 1), b2 + hstepB, voffB); PG8_STAGE(PG8_SA(0, 0), a2, voffA);
.LBB0_1232:
	s_add_u32 s36, s80, 0x100
	s_addc_u32 s37, s81, 0
	s_ashr_i32 s73, s72, 31
	s_lshl_b64 s[4:5], s[72:73], 20
	s_add_u32 s78, s0, s4
	s_addc_u32 s79, s1, s5
	s_and_b64 s[4:5], s[46:47], exec
	s_cselect_b32 s4, s79, s69
	s_cselect_b32 s5, s78, s68
	s_ashr_i32 s71, s70, 31
	s_lshl_b64 s[6:7], s[70:71], 20
	s_add_u32 s76, s34, s6
	s_addc_u32 s77, s35, s7
	s_and_b64 s[6:7], s[46:47], exec
	s_cselect_b32 s6, s77, s81
	s_cselect_b32 s7, s76, s80
	s_add_u32 s8, s68, 0x80080
	s_addc_u32 s9, s69, 0
	v_lshl_add_u64 v[140:141], s[8:9], 0, v[136:137]
	v_lshl_add_u64 v[142:143], s[8:9], 0, v[138:139]
	s_mov_b32 s8, -2
	s_mov_b64 s[80:81], 0
	v_add_u32_e32 v186, 0x10000, v145
	v_add_u32_e32 v187, 0x14000, v145
	v_add_u32_e32 v198, 0x18000, v145
	v_add_u32_e32 v199, 0x1c000, v145
	s_add_u32 s9, s68, s80
	s_addc_u32 s10, s69, s81
	s_add_u32 s9, s9, 0x100
	s_addc_u32 s10, s10, 0
	s_add_u32 s100, s9, 0x7ff80
	s_addc_u32 s101, s10, 0
	s_add_u32 s11, s36, s80
	s_addc_u32 s12, s37, s81
	s_add_i32 s13, 0, 0x10000
	s_cmpk_eq_i32 s80, 0xf00
	s_cselect_b32 s93, s4, s10
	s_cselect_b32 s92, s5, s9
	s_cselect_b32 s85, s6, s12
	s_cselect_b32 s84, s7, s11
	s_add_i32 s9, 0, 0x14000
	ds_read_b128 v[152:155], v186
	ds_read_b128 v[156:159], v186 offset:1024
	ds_read_b128 v[160:163], v186 offset:2048
	ds_read_b128 v[164:167], v186 offset:3072
	ds_read_b128 v[168:171], v187
	ds_read_b128 v[172:175], v187 offset:1024
	ds_read_b128 v[176:179], v187 offset:2048
	ds_read_b128 v[180:183], v187 offset:3072
	s_add_i32 m0, s51, 0xc000
	ds_read_b128 v[206:209], v151
	ds_read_b128 v[210:213], v151 offset:1024
	ds_read_b128 v[214:217], v151 offset:2048
	ds_read_b128 v[218:221], v151 offset:3072
	ds_read_b128 v[236:239], v151 offset:4096
	ds_read_b128 v[240:243], v151 offset:5120
	ds_read_b128 v[244:247], v151 offset:6144
	ds_read_b128 v[194:197], v151 offset:7168
	global_load_lds_dwordx4 v136, s[100:101]
	s_add_i32 m0, s51, 0xe000
	s_nop 0
	global_load_lds_dwordx4 v138, s[100:101]
	s_waitcnt vmcnt(8)
	s_waitcnt lgkmcnt(0)
	s_barrier
	v_mfma_f32_16x16x32_bf16 v[126:129], v[152:155], v[206:209], 0
	v_mfma_f32_16x16x32_bf16 v[122:125], v[160:163], v[206:209], 0
	v_mfma_f32_16x16x32_bf16 v[118:121], v[152:155], v[214:217], 0
	v_mfma_f32_16x16x32_bf16 v[114:117], v[160:163], v[214:217], 0
	v_mfma_f32_16x16x32_bf16 v[110:113], v[152:155], v[236:239], 0
	v_mfma_f32_16x16x32_bf16 v[106:109], v[160:163], v[236:239], 0
	v_mfma_f32_16x16x32_bf16 v[102:105], v[152:155], v[244:247], 0
	v_mfma_f32_16x16x32_bf16 v[98:101], v[160:163], v[244:247], 0
	v_mfma_f32_16x16x32_bf16 v[126:129], v[156:159], v[210:213], v[126:129]
	v_mfma_f32_16x16x32_bf16 v[122:125], v[164:167], v[210:213], v[122:125]
	v_mfma_f32_16x16x32_bf16 v[118:121], v[156:159], v[218:221], v[118:121]
	v_mfma_f32_16x16x32_bf16 v[114:117], v[164:167], v[218:221], v[114:117]
	v_mfma_f32_16x16x32_bf16 v[110:113], v[156:159], v[240:243], v[110:113]
	v_mfma_f32_16x16x32_bf16 v[106:109], v[164:167], v[240:243], v[106:109]
	v_mfma_f32_16x16x32_bf16 v[102:105], v[156:159], v[194:197], v[102:105]
	v_mfma_f32_16x16x32_bf16 v[98:101], v[164:167], v[194:197], v[98:101]
	v_mfma_f32_16x16x32_bf16 v[94:97], v[168:171], v[206:209], 0
	v_mfma_f32_16x16x32_bf16 v[90:93], v[176:179], v[206:209], 0
	v_mfma_f32_16x16x32_bf16 v[86:89], v[168:171], v[214:217], 0
	v_mfma_f32_16x16x32_bf16 v[82:85], v[176:179], v[214:217], 0
	v_mfma_f32_16x16x32_bf16 v[78:81], v[168:171], v[236:239], 0
	v_mfma_f32_16x16x32_bf16 v[74:77], v[176:179], v[236:239], 0
	v_mfma_f32_16x16x32_bf16 v[70:73], v[168:171], v[244:247], 0
	v_mfma_f32_16x16x32_bf16 v[66:69], v[176:179], v[244:247], 0
	v_mfma_f32_16x16x32_bf16 v[94:97], v[172:175], v[210:213], v[94:97]
	v_mfma_f32_16x16x32_bf16 v[90:93], v[180:183], v[210:213], v[90:93]
	v_mfma_f32_16x16x32_bf16 v[86:89], v[172:175], v[218:221], v[86:89]
	v_mfma_f32_16x16x32_bf16 v[82:85], v[180:183], v[218:221], v[82:85]
	v_mfma_f32_16x16x32_bf16 v[78:81], v[172:175], v[240:243], v[78:81]
	v_mfma_f32_16x16x32_bf16 v[74:77], v[180:183], v[240:243], v[74:77]
	v_mfma_f32_16x16x32_bf16 v[70:73], v[172:175], v[194:197], v[70:73]
	v_mfma_f32_16x16x32_bf16 v[66:69], v[180:183], v[194:197], v[66:69]
	s_barrier
	s_add_i32 s10, s13, s42
	s_mov_b32 m0, s10
	ds_read_b128 v[194:197], v151 offset:16384
	ds_read_b128 v[206:209], v151 offset:17408
	ds_read_b128 v[210:213], v151 offset:18432
	ds_read_b128 v[214:217], v151 offset:19456
	ds_read_b128 v[218:221], v151 offset:20480
	ds_read_b128 v[236:239], v151 offset:21504
	ds_read_b128 v[240:243], v151 offset:22528
	ds_read_b128 v[244:247], v151 offset:23552
	global_load_lds_dwordx4 v130, s[84:85]
	s_add_i32 m0, s10, 0x2000
	s_add_u32 s10, s84, 0x20000
	s_addc_u32 s11, s85, 0
	s_add_i32 s9, s9, s42
	global_load_lds_dwordx4 v134, s[84:85]
	s_mov_b32 m0, s9
	s_nop 0
	global_load_lds_dwordx4 v130, s[10:11]
	s_add_i32 m0, s9, 0x2000
	s_nop 0
	global_load_lds_dwordx4 v134, s[10:11]
	s_mov_b32 m0, s51
	s_nop 0
	global_load_lds_dwordx4 v190, s[92:93]
	s_mov_b32 m0, s67
	s_nop 0
	global_load_lds_dwordx4 v132, s[92:93]
	s_waitcnt vmcnt(8)
	s_waitcnt lgkmcnt(0)
	s_barrier
; #define PG8_STAGE(bufoff, gbase, voff) do { _Pragma("unroll") for (int _i = 0; _i < 2; ++_i) \
;         __builtin_amdgcn_global_load_lds((const unsigned*)((const char*)(gbase) + (voff)[_i]), (PG8_LAS unsigned*)(lds + (bufoff) + ldsw + _i * 8192), 16, 0, 0); } while (0)
; #define PG8_LDA(dst, b, h) do { _Pragma("unroll") for (int m = 0; m < 4; ++m) _Pragma("unroll") for (int k = 0; k < 2; ++k) dst[m][k] = *(const PG8_LAS bf16x8*)(lds + PG8_SA(b, h) + aoff + m * 2048 + k * 1024); } while (0)
; #define PG8_LDB(dst, b, h) do { _Pragma("unroll") for (int n = 0; n < 2; ++n) _Pragma("unroll") for (int k = 0; k < 2; ++k) dst[n][k] = *(const PG8_LAS bf16x8*)(lds + PG8_SB(b, h) + boff + n * 2048 + k * 1024); } while (0)
; #define PG8_MMA(ai, bj, At, Bt) do { __builtin_amdgcn_s_setprio(1); _Pragma("unroll") for (int m = 0; m < 4; ++m) _Pragma("unroll") for (int n = 0; n < 2; ++n) _Pragma("unroll") for (int k = 0; k < 2; ++k) \
;         acc[ai][bj][m][n] = __builtin_amdgcn_mfma_f32_16x16x32_bf16(Bt[n][k], At[m][k], acc[ai][bj][m][n], 0, 0, 0); __builtin_amdgcn_s_setprio(0); } while (0)
; #define PG8_WAIT_V(n) asm volatile("s_waitcnt vmcnt(" #n ")" ::: "memory")
; #define PG8_WAIT_L(n) asm volatile("s_waitcnt lgkmcnt(" #n ")" ::: "memory")
; #define PG8_BAR __builtin_amdgcn_s_barrier()
; #define PG8_SCHED __builtin_amdgcn_sched_barrier(0)
; template <class Epi, class Sched, bool ALIGN_EPI = false, bool SP2 = false>
; __device__ __forceinline__ void gemm_phase(PG8_LAS unsigned char* lds, const Gemm g, const Sched& S, const Epi& E) {
;     ...
;             PG8_WAIT_V(8); PG8_WAIT_L(0); PG8_BAR; PG8_MMA(1, 0, At, B0); PG8_MMA(1, 1, At, B1); PG8_BAR; PG8_SCHED;
;             PG8_LDB(B0, 1, 0); PG8_LDB(B1, 1, 1); PG8_SCHED; PG8_LDA(At, 1, 0); PG8_STAGE(PG8_SA(0, 1), a2 + hstep, voffA);
;             PG8_WAIT_V(8); PG8_WAIT_L(0); PG8_BAR; PG8_MMA(0, 0, At, B0); PG8_MMA(0, 1, At, B1); PG8_BAR; PG8_SCHED;
	v_mfma_f32_16x16x32_bf16 v[62:65], v[152:155], v[194:197], 0
	v_mfma_f32_16x16x32_bf16 v[58:61], v[160:163], v[194:197], 0
	v_mfma_f32_16x16x32_bf16 v[54:57], v[152:155], v[210:213], 0
	v_mfma_f32_16x16x32_bf16 v[50:53], v[160:163], v[210:213], 0
	v_mfma_f32_16x16x32_bf16 v[46:49], v[152:155], v[218:221], 0
	v_mfma_f32_16x16x32_bf16 v[42:45], v[160:163], v[218:221], 0
	v_mfma_f32_16x16x32_bf16 v[38:41], v[152:155], v[240:243], 0
	v_mfma_f32_16x16x32_bf16 v[34:37], v[160:163], v[240:243], 0
	v_mfma_f32_16x16x32_bf16 v[62:65], v[156:159], v[206:209], v[62:65]
	v_mfma_f32_16x16x32_bf16 v[58:61], v[164:167], v[206:209], v[58:61]
	v_mfma_f32_16x16x32_bf16 v[54:57], v[156:159], v[214:217], v[54:57]
	v_mfma_f32_16x16x32_bf16 v[50:53], v[164:167], v[214:217], v[50:53]
	v_mfma_f32_16x16x32_bf16 v[46:49], v[156:159], v[236:239], v[46:49]
	v_mfma_f32_16x16x32_bf16 v[42:45], v[164:167], v[236:239], v[42:45]
	v_mfma_f32_16x16x32_bf16 v[38:41], v[156:159], v[244:247], v[38:41]
	v_mfma_f32_16x16x32_bf16 v[34:37], v[164:167], v[244:247], v[34:37]
	v_mfma_f32_16x16x32_bf16 v[30:33], v[168:171], v[194:197], 0
	v_mfma_f32_16x16x32_bf16 v[26:29], v[176:179], v[194:197], 0
	v_mfma_f32_16x16x32_bf16 v[22:25], v[168:171], v[210:213], 0
	v_mfma_f32_16x16x32_bf16 v[18:21], v[176:179], v[210:213], 0
	v_mfma_f32_16x16x32_bf16 v[14:17], v[168:171], v[218:221], 0
	v_mfma_f32_16x16x32_bf16 v[10:13], v[176:179], v[218:221], 0
	v_mfma_f32_16x16x32_bf16 v[6:9], v[168:171], v[240:243], 0
	v_mfma_f32_16x16x32_bf16 v[2:5], v[176:179], v[240:243], 0
	v_mfma_f32_16x16x32_bf16 v[30:33], v[172:175], v[206:209], v[30:33]
	v_mfma_f32_16x16x32_bf16 v[26:29], v[180:183], v[206:209], v[26:29]
	v_mfma_f32_16x16x32_bf16 v[22:25], v[172:175], v[214:217], v[22:25]
	v_mfma_f32_16x16x32_bf16 v[18:21], v[180:183], v[214:217], v[18:21]
	v_mfma_f32_16x16x32_bf16 v[14:17], v[172:175], v[236:239], v[14:17]
	v_mfma_f32_16x16x32_bf16 v[10:13], v[180:183], v[236:239], v[10:13]
	v_mfma_f32_16x16x32_bf16 v[6:9], v[172:175], v[244:247], v[6:9]
	v_mfma_f32_16x16x32_bf16 v[2:5], v[180:183], v[244:247], v[2:5]
	s_barrier
	s_add_i32 s9, 0, 0x18000
	s_add_i32 s12, 0, 0x1c000
	ds_read_b128 v[152:155], v198
	ds_read_b128 v[156:159], v198 offset:1024
	ds_read_b128 v[160:163], v198 offset:2048
	ds_read_b128 v[164:167], v198 offset:3072
	ds_read_b128 v[168:171], v199
	ds_read_b128 v[172:175], v199 offset:1024
	ds_read_b128 v[176:179], v199 offset:2048
	ds_read_b128 v[180:183], v199 offset:3072
	s_add_u32 s10, s92, 0x80000
	s_addc_u32 s11, s93, 0
	s_mov_b32 m0, s74
	ds_read_b128 v[194:197], v151 offset:32768
	ds_read_b128 v[206:209], v151 offset:33792
	ds_read_b128 v[210:213], v151 offset:34816
	ds_read_b128 v[214:217], v151 offset:35840
	ds_read_b128 v[218:221], v151 offset:36864
	ds_read_b128 v[236:239], v151 offset:37888
	ds_read_b128 v[240:243], v151 offset:38912
	ds_read_b128 v[244:247], v151 offset:39936
	global_load_lds_dwordx4 v190, s[10:11]
	s_mov_b32 m0, s75
	s_nop 0
	global_load_lds_dwordx4 v132, s[10:11]
	s_waitcnt vmcnt(8)
	s_waitcnt lgkmcnt(0)
	s_barrier
	v_mfma_f32_16x16x32_bf16 v[126:129], v[152:155], v[194:197], v[126:129]
	v_mfma_f32_16x16x32_bf16 v[122:125], v[160:163], v[194:197], v[122:125]
	v_mfma_f32_16x16x32_bf16 v[118:121], v[152:155], v[210:213], v[118:121]
	v_mfma_f32_16x16x32_bf16 v[114:117], v[160:163], v[210:213], v[114:117]
	v_mfma_f32_16x16x32_bf16 v[110:113], v[152:155], v[218:221], v[110:113]
	v_mfma_f32_16x16x32_bf16 v[106:109], v[160:163], v[218:221], v[106:109]
	v_mfma_f32_16x16x32_bf16 v[102:105], v[152:155], v[240:243], v[102:105]
	v_mfma_f32_16x16x32_bf16 v[98:101], v[160:163], v[240:243], v[98:101]
	v_mfma_f32_16x16x32_bf16 v[126:129], v[156:159], v[206:209], v[126:129]
	v_mfma_f32_16x16x32_bf16 v[122:125], v[164:167], v[206:209], v[122:125]
	v_mfma_f32_16x16x32_bf16 v[118:121], v[156:159], v[214:217], v[118:121]
	v_mfma_f32_16x16x32_bf16 v[114:117], v[164:167], v[214:217], v[114:117]
	v_mfma_f32_16x16x32_bf16 v[110:113], v[156:159], v[236:239], v[110:113]
	v_mfma_f32_16x16x32_bf16 v[106:109], v[164:167], v[236:239], v[106:109]
	v_mfma_f32_16x16x32_bf16 v[102:105], v[156:159], v[244:247], v[102:105]
	v_mfma_f32_16x16x32_bf16 v[98:101], v[164:167], v[244:247], v[98:101]
	v_mfma_f32_16x16x32_bf16 v[94:97], v[168:171], v[194:197], v[94:97]
	v_mfma_f32_16x16x32_bf16 v[90:93], v[176:179], v[194:197], v[90:93]
	v_mfma_f32_16x16x32_bf16 v[86:89], v[168:171], v[210:213], v[86:89]
	v_mfma_f32_16x16x32_bf16 v[82:85], v[176:179], v[210:213], v[82:85]
	v_mfma_f32_16x16x32_bf16 v[78:81], v[168:171], v[218:221], v[78:81]
	v_mfma_f32_16x16x32_bf16 v[74:77], v[176:179], v[218:221], v[74:77]
	v_mfma_f32_16x16x32_bf16 v[70:73], v[168:171], v[240:243], v[70:73]
	v_mfma_f32_16x16x32_bf16 v[66:69], v[176:179], v[240:243], v[66:69]
	v_mfma_f32_16x16x32_bf16 v[94:97], v[172:175], v[206:209], v[94:97]
	v_mfma_f32_16x16x32_bf16 v[90:93], v[180:183], v[206:209], v[90:93]
	v_mfma_f32_16x16x32_bf16 v[86:89], v[172:175], v[214:217], v[86:89]
	v_mfma_f32_16x16x32_bf16 v[82:85], v[180:183], v[214:217], v[82:85]
	v_mfma_f32_16x16x32_bf16 v[78:81], v[172:175], v[236:239], v[78:81]
	v_mfma_f32_16x16x32_bf16 v[74:77], v[180:183], v[236:239], v[74:77]
	v_mfma_f32_16x16x32_bf16 v[70:73], v[172:175], v[244:247], v[70:73]
	v_mfma_f32_16x16x32_bf16 v[66:69], v[180:183], v[244:247], v[66:69]
	s_barrier
; #define PG8_STAGE(bufoff, gbase, voff) do { _Pragma("unroll") for (int _i = 0; _i < 2; ++_i) \
;         __builtin_amdgcn_global_load_lds((const unsigned*)((const char*)(gbase) + (voff)[_i]), (PG8_LAS unsigned*)(lds + (bufoff) + ldsw + _i * 8192), 16, 0, 0); } while (0)
; #define PG8_LDA(dst, b, h) do { _Pragma("unroll") for (int m = 0; m < 4; ++m) _Pragma("unroll") for (int k = 0; k < 2; ++k) dst[m][k] = *(const PG8_LAS bf16x8*)(lds + PG8_SA(b, h) + aoff + m * 2048 + k * 1024); } while (0)
; #define PG8_MMA(ai, bj, At, Bt) do { __builtin_amdgcn_s_setprio(1); _Pragma("unroll") for (int m = 0; m < 4; ++m) _Pragma("unroll") for (int n = 0; n < 2; ++n) _Pragma("unroll") for (int k = 0; k < 2; ++k) \
;         acc[ai][bj][m][n] = __builtin_amdgcn_mfma_f32_16x16x32_bf16(Bt[n][k], At[m][k], acc[ai][bj][m][n], 0, 0, 0); __builtin_amdgcn_s_setprio(0); } while (0)
; #define PG8_WAIT_V(n) asm volatile("s_waitcnt vmcnt(" #n ")" ::: "memory")
; #define PG8_WAIT_L(n) asm volatile("s_waitcnt lgkmcnt(" #n ")" ::: "memory")
; #define PG8_BAR __builtin_amdgcn_s_barrier()
; #define PG8_SCHED __builtin_amdgcn_sched_barrier(0)
; template <class Epi, class Sched, bool ALIGN_EPI = false, bool SP2 = false>
; __device__ __forceinline__ void gemm_phase(PG8_LAS unsigned char* lds, const Gemm g, const Sched& S, const Epi& E) {
;     ...
;             PG8_LDA(At, 1, 1); PG8_STAGE(PG8_SB(1, 0), b3, voffB); PG8_STAGE(PG8_SB(1, 1), b3 + hstepB, voffB); PG8_STAGE(PG8_SA(1, 0), a3, voffA);
;             PG8_WAIT_V(8); PG8_WAIT_L(0); PG8_BAR; PG8_MMA(1, 0, At, B0); PG8_MMA(1, 1, At, B1); PG8_BAR; PG8_SCHED;
	s_add_i32 s9, s9, s42
	s_mov_b32 m0, s9
	ds_read_b128 v[194:197], v151 offset:49152
	ds_read_b128 v[206:209], v151 offset:50176
	ds_read_b128 v[210:213], v151 offset:51200
	ds_read_b128 v[214:217], v151 offset:52224
	ds_read_b128 v[218:221], v151 offset:53248
	ds_read_b128 v[236:239], v151 offset:54272
	ds_read_b128 v[240:243], v151 offset:55296
	ds_read_b128 v[244:247], v151 offset:56320
	s_add_u32 s100, s84, s60
	s_addc_u32 s101, s85, s61
	global_load_lds_dwordx4 v130, s[100:101]
	s_add_i32 m0, s9, 0x2000
	s_add_u32 s10, s84, 0x20080
	s_addc_u32 s11, s85, 0
	s_add_i32 s9, s12, s42
	global_load_lds_dwordx4 v134, s[100:101]
	s_mov_b32 m0, s9
	s_nop 0
	global_load_lds_dwordx4 v130, s[10:11]
	s_add_i32 m0, s9, 0x2000
	s_nop 0
	global_load_lds_dwordx4 v134, s[10:11]
	s_mov_b32 m0, s82
	s_add_u32 s100, s92, s60
	s_addc_u32 s101, s93, s61
	global_load_lds_dwordx4 v190, s[100:101]
	s_mov_b32 m0, s86
	s_nop 0
	global_load_lds_dwordx4 v132, s[100:101]
	s_waitcnt vmcnt(8)
	s_waitcnt lgkmcnt(0)
	s_barrier
	v_mfma_f32_16x16x32_bf16 v[62:65], v[152:155], v[194:197], v[62:65]
	v_mfma_f32_16x16x32_bf16 v[58:61], v[160:163], v[194:197], v[58:61]
	v_mfma_f32_16x16x32_bf16 v[54:57], v[152:155], v[210:213], v[54:57]
	v_mfma_f32_16x16x32_bf16 v[50:53], v[160:163], v[210:213], v[50:53]
	v_mfma_f32_16x16x32_bf16 v[46:49], v[152:155], v[218:221], v[46:49]
	v_mfma_f32_16x16x32_bf16 v[42:45], v[160:163], v[218:221], v[42:45]
	v_mfma_f32_16x16x32_bf16 v[38:41], v[152:155], v[240:243], v[38:41]
	v_mfma_f32_16x16x32_bf16 v[34:37], v[160:163], v[240:243], v[34:37]
	v_mfma_f32_16x16x32_bf16 v[62:65], v[156:159], v[206:209], v[62:65]
	v_mfma_f32_16x16x32_bf16 v[58:61], v[164:167], v[206:209], v[58:61]
	v_mfma_f32_16x16x32_bf16 v[54:57], v[156:159], v[214:217], v[54:57]
	v_mfma_f32_16x16x32_bf16 v[50:53], v[164:167], v[214:217], v[50:53]
	v_mfma_f32_16x16x32_bf16 v[46:49], v[156:159], v[236:239], v[46:49]
	v_mfma_f32_16x16x32_bf16 v[42:45], v[164:167], v[236:239], v[42:45]
	v_mfma_f32_16x16x32_bf16 v[38:41], v[156:159], v[244:247], v[38:41]
	v_mfma_f32_16x16x32_bf16 v[34:37], v[164:167], v[244:247], v[34:37]
	v_mfma_f32_16x16x32_bf16 v[30:33], v[168:171], v[194:197], v[30:33]
	v_mfma_f32_16x16x32_bf16 v[26:29], v[176:179], v[194:197], v[26:29]
	v_mfma_f32_16x16x32_bf16 v[22:25], v[168:171], v[210:213], v[22:25]
	v_mfma_f32_16x16x32_bf16 v[18:21], v[176:179], v[210:213], v[18:21]
	v_mfma_f32_16x16x32_bf16 v[14:17], v[168:171], v[218:221], v[14:17]
	v_mfma_f32_16x16x32_bf16 v[10:13], v[176:179], v[218:221], v[10:13]
	v_mfma_f32_16x16x32_bf16 v[6:9], v[168:171], v[240:243], v[6:9]
	v_mfma_f32_16x16x32_bf16 v[2:5], v[176:179], v[240:243], v[2:5]
	v_mfma_f32_16x16x32_bf16 v[30:33], v[172:175], v[206:209], v[30:33]
	v_mfma_f32_16x16x32_bf16 v[26:29], v[180:183], v[206:209], v[26:29]
	v_mfma_f32_16x16x32_bf16 v[22:25], v[172:175], v[214:217], v[22:25]
	v_mfma_f32_16x16x32_bf16 v[18:21], v[180:183], v[214:217], v[18:21]
	v_mfma_f32_16x16x32_bf16 v[14:17], v[172:175], v[236:239], v[14:17]
	v_mfma_f32_16x16x32_bf16 v[10:13], v[180:183], v[236:239], v[10:13]
	v_mfma_f32_16x16x32_bf16 v[6:9], v[172:175], v[244:247], v[6:9]
	v_mfma_f32_16x16x32_bf16 v[2:5], v[180:183], v[244:247], v[2:5]
	s_barrier
	s_add_i32 s8, s8, 2
	s_add_u32 s80, s80, 0x100
	s_addc_u32 s81, s81, 0
	s_cmp_gt_u32 s8, 29
